# K-loops of P3/P4/P5/P6: the redundant s_waitcnt lgkmcnt(0) right after the post-barrier s_setprio 1 deleted (the same wait already precedes the barrier)
# speedup vs baseline: 1.0057x; 1.0057x over previous
; #define PG8_STAGE(bufoff, gbase, voff) do { _Pragma("unroll") for (int _i = 0; _i < 2; ++_i) { unsigned vo_ = (voff)[_i]; if constexpr (FP8) asm volatile("" : "+v"(vo_)); \
;         __builtin_amdgcn_global_load_lds((const unsigned*)((const char*)(gbase) + vo_), (PG8_LAS unsigned*)(lds + (bufoff) + ldsw + _i * 8192), 16, 0, 0); } } while (0)
; #define PG8_LDA(dst, b, h) do { _Pragma("unroll") for (int m = 0; m < 4; ++m) _Pragma("unroll") for (int k = 0; k < 2; ++k) dst[m][k] = *(const PG8_LAS bf16x8*)(lds + PG8_SA(b, h) + aoff + m * 2048 + k * 1024); } while (0)
; #define PG8_LDB(dst, b, h) do { _Pragma("unroll") for (int n = 0; n < 2; ++n) _Pragma("unroll") for (int k = 0; k < 2; ++k) dst[n][k] = *(const PG8_LAS bf16x8*)(lds + PG8_SB(b, h) + boff + n * 2048 + k * 1024); } while (0)
; #define PG8_WAIT_V(n) asm volatile("s_waitcnt vmcnt(" #n ")" ::: "memory")
; #define PG8_WAIT_L(n) asm volatile("s_waitcnt lgkmcnt(" #n ")" ::: "memory")
; #define PG8_BAR __builtin_amdgcn_s_barrier()
; #define PG8_SCHED __builtin_amdgcn_sched_barrier(0)
; template <class Epi, class Sched, bool ALIGN_EPI = false, bool SP2 = false, bool FP8 = false>
; __device__ __forceinline__ void gemm_phase(PG8_LAS unsigned char* lds, const Gemm g, const Sched& S, const Epi& E) {
;     ...
;             PG8_LDB(B0, 0, 0); PG8_LDB(B1, 0, 1); PG8_SCHED; PG8_LDA(At, 0, 0); PG8_STAGE(PG8_SA(1, 1), a1 + hstep, voffA);
;             PG8_WAIT_V(8); PG8_WAIT_L(0); PG8_BAR; PG8_MMA(0, 0, At, B0); PG8_MMA(0, 1, At, B1); PG8_BAR; PG8_SCHED;
;             PG8_LDA(At, 0, 1); PG8_STAGE(PG8_SB(0, 0), b2, voffB); PG8_STAGE(PG8_SB(0, 1), b2 + hstep, voffB); PG8_STAGE(PG8_SA(0, 0), a2, voffA);
;             PG8_WAIT_V(8); PG8_WAIT_L(0); PG8_BAR; PG8_MMA(1, 0, At, B0); PG8_MMA(1, 1, At, B1); PG8_BAR; PG8_SCHED;
.LBB0_305:
	s_add_u32 s52, s10, 0xfffe8080
	s_addc_u32 s53, s11, -1
	s_and_b64 s[0:1], s[62:63], exec
	s_cselect_b32 s65, s5, s53
	s_cselect_b32 s64, s4, s52
	s_add_i32 s52, 0, 0x10000
	v_add_u32_e32 v128, s52, v152
	ds_read_b128 v[134:137], v128
	ds_read_b128 v[138:141], v128 offset:1024
	ds_read_b128 v[156:159], v128 offset:2048
	ds_read_b128 v[160:163], v128 offset:3072
	v_add_u32_e32 v128, s84, v152
	ds_read_b128 v[164:167], v128
	ds_read_b128 v[168:171], v128 offset:1024
	ds_read_b128 v[178:181], v128 offset:2048
	ds_read_b128 v[182:185], v128 offset:3072
	s_and_b64 s[0:1], s[62:63], exec
	s_cselect_b32 s63, s61, s90
	s_cselect_b32 s62, s60, s89
	v_mov_b32_e32 v128, v146
	ds_read_b128 v[186:189], v153
	ds_read_b128 v[190:193], v153 offset:1024
	ds_read_b128 v[198:201], v153 offset:2048
	ds_read_b128 v[202:205], v153 offset:3072
	ds_read_b128 v[206:209], v153 offset:4096
	ds_read_b128 v[210:213], v153 offset:5120
	ds_read_b128 v[214:217], v153 offset:6144
	ds_read_b128 v[218:221], v153 offset:7168
	s_add_i32 m0, s68, 0xc000
	s_nop 0
	global_load_lds_dwordx4 v128, s[10:11]
	v_mov_b32_e32 v128, v148
	s_add_i32 m0, s68, 0xe000
	s_nop 0
	global_load_lds_dwordx4 v128, s[10:11]
	s_waitcnt vmcnt(8)
	s_waitcnt lgkmcnt(0)
	s_barrier
	s_setprio 1
	v_mfma_scale_f32_16x16x128_f8f6f4 v[112:115], v[134:141], v[186:193], v[112:115], v154, v154 op_sel_hi:[0,0,0]
	v_mfma_scale_f32_16x16x128_f8f6f4 v[116:119], v[156:163], v[186:193], v[116:119], v154, v154 op_sel_hi:[0,0,0]
	v_mfma_scale_f32_16x16x128_f8f6f4 v[96:99], v[134:141], v[198:205], v[96:99], v154, v154 op_sel_hi:[0,0,0]
	v_mfma_scale_f32_16x16x128_f8f6f4 v[100:103], v[156:163], v[198:205], v[100:103], v154, v154 op_sel_hi:[0,0,0]
	v_mfma_scale_f32_16x16x128_f8f6f4 v[142:145], v[134:141], v[206:213], v[80:83], v154, v154 op_sel_hi:[0,0,0]
	v_mfma_scale_f32_16x16x128_f8f6f4 v[172:175], v[156:163], v[206:213], v[84:87], v154, v154 op_sel_hi:[0,0,0]
	v_mfma_scale_f32_16x16x128_f8f6f4 v[194:197], v[134:141], v[214:221], v[64:67], v154, v154 op_sel_hi:[0,0,0]
	v_mfma_scale_f32_16x16x128_f8f6f4 v[222:225], v[156:163], v[214:221], v[68:71], v154, v154 op_sel_hi:[0,0,0]
	s_setprio 0
	s_setprio 1
	v_mfma_scale_f32_16x16x128_f8f6f4 v[120:123], v[164:171], v[186:193], v[120:123], v154, v154 op_sel_hi:[0,0,0]
	v_mfma_scale_f32_16x16x128_f8f6f4 v[124:127], v[178:185], v[186:193], v[124:127], v154, v154 op_sel_hi:[0,0,0]
	v_mfma_scale_f32_16x16x128_f8f6f4 v[104:107], v[164:171], v[198:205], v[104:107], v154, v154 op_sel_hi:[0,0,0]
	v_mfma_scale_f32_16x16x128_f8f6f4 v[108:111], v[178:185], v[198:205], v[108:111], v154, v154 op_sel_hi:[0,0,0]
	v_mfma_scale_f32_16x16x128_f8f6f4 v[186:189], v[164:171], v[206:213], v[88:91], v154, v154 op_sel_hi:[0,0,0]
	v_mfma_scale_f32_16x16x128_f8f6f4 v[190:193], v[178:185], v[206:213], v[92:95], v154, v154 op_sel_hi:[0,0,0]
	v_mfma_scale_f32_16x16x128_f8f6f4 v[198:201], v[164:171], v[214:221], v[72:75], v154, v154 op_sel_hi:[0,0,0]
	v_mfma_scale_f32_16x16x128_f8f6f4 v[202:205], v[178:185], v[214:221], v[76:79], v154, v154 op_sel_hi:[0,0,0]
	s_setprio 0
	s_barrier
	v_mov_b32_e32 v128, v147
	s_add_i32 s0, s52, s66
	ds_read_b128 v[64:67], v153 offset:16384
	ds_read_b128 v[68:71], v153 offset:17408
	ds_read_b128 v[72:75], v153 offset:18432
	ds_read_b128 v[76:79], v153 offset:19456
	ds_read_b128 v[80:83], v153 offset:20480
	ds_read_b128 v[84:87], v153 offset:21504
	ds_read_b128 v[88:91], v153 offset:22528
	ds_read_b128 v[92:95], v153 offset:23552
	s_mov_b32 m0, s0
	s_nop 0
	global_load_lds_dwordx4 v128, s[62:63]
	v_mov_b32_e32 v128, v149
	s_add_i32 m0, s0, 0x2000
	s_add_u32 s0, s62, 0x18000
	global_load_lds_dwordx4 v128, s[62:63]
	s_addc_u32 s1, s63, 0
	v_mov_b32_e32 v128, v147
	s_add_i32 s52, s84, s66
	s_mov_b32 m0, s52
	s_nop 0
	global_load_lds_dwordx4 v128, s[0:1]
	v_mov_b32_e32 v128, v149
	s_add_i32 m0, s52, 0x2000
	s_nop 0
	global_load_lds_dwordx4 v128, s[0:1]
	v_mov_b32_e32 v128, v146
	s_mov_b32 m0, s68
	s_nop 0
	global_load_lds_dwordx4 v128, s[64:65]
	v_mov_b32_e32 v128, v148
	s_mov_b32 m0, s69
	s_nop 0
	global_load_lds_dwordx4 v128, s[64:65]
	s_waitcnt vmcnt(8)
	s_waitcnt lgkmcnt(0)
	s_barrier
	s_setprio 1
	v_mfma_scale_f32_16x16x128_f8f6f4 v[48:51], v[134:141], v[64:71], v[48:51], v154, v154 op_sel_hi:[0,0,0]
	v_mfma_scale_f32_16x16x128_f8f6f4 v[52:55], v[156:163], v[64:71], v[52:55], v154, v154 op_sel_hi:[0,0,0]
	v_mfma_scale_f32_16x16x128_f8f6f4 v[206:209], v[134:141], v[72:79], v[32:35], v154, v154 op_sel_hi:[0,0,0]
	v_mfma_scale_f32_16x16x128_f8f6f4 v[210:213], v[156:163], v[72:79], v[36:39], v154, v154 op_sel_hi:[0,0,0]
	v_mfma_scale_f32_16x16x128_f8f6f4 v[214:217], v[134:141], v[80:87], v[16:19], v154, v154 op_sel_hi:[0,0,0]
	v_mfma_scale_f32_16x16x128_f8f6f4 v[218:221], v[156:163], v[80:87], v[20:23], v154, v154 op_sel_hi:[0,0,0]
	v_mfma_scale_f32_16x16x128_f8f6f4 v[226:229], v[134:141], v[88:95], v[4:7], v154, v154 op_sel_hi:[0,0,0]
	v_mfma_scale_f32_16x16x128_f8f6f4 v[230:233], v[156:163], v[88:95], v[8:11], v154, v154 op_sel_hi:[0,0,0]
	s_setprio 0
	s_setprio 1
	v_mfma_scale_f32_16x16x128_f8f6f4 v[56:59], v[164:171], v[64:71], v[56:59], v154, v154 op_sel_hi:[0,0,0]
	v_mfma_scale_f32_16x16x128_f8f6f4 v[60:63], v[178:185], v[64:71], v[60:63], v154, v154 op_sel_hi:[0,0,0]
	v_mfma_scale_f32_16x16x128_f8f6f4 v[234:237], v[164:171], v[72:79], v[40:43], v154, v154 op_sel_hi:[0,0,0]
	v_mfma_scale_f32_16x16x128_f8f6f4 v[238:241], v[178:185], v[72:79], v[44:47], v154, v154 op_sel_hi:[0,0,0]
	v_mfma_scale_f32_16x16x128_f8f6f4 v[242:245], v[164:171], v[80:87], v[24:27], v154, v154 op_sel_hi:[0,0,0]
	v_mfma_scale_f32_16x16x128_f8f6f4 v[246:249], v[178:185], v[80:87], v[28:31], v154, v154 op_sel_hi:[0,0,0]
	v_mfma_scale_f32_16x16x128_f8f6f4 v[250:253], v[164:171], v[88:95], v[12:15], v154, v154 op_sel_hi:[0,0,0]
	v_mfma_scale_f32_16x16x128_f8f6f4 v[130:133], v[178:185], v[88:95], v[0:3], v154, v154 op_sel_hi:[0,0,0]
	s_setprio 0
	s_barrier
; #define PG8_STAGE(bufoff, gbase, voff) do { _Pragma("unroll") for (int _i = 0; _i < 2; ++_i) { unsigned vo_ = (voff)[_i]; if constexpr (FP8) asm volatile("" : "+v"(vo_)); \
;         __builtin_amdgcn_global_load_lds((const unsigned*)((const char*)(gbase) + vo_), (PG8_LAS unsigned*)(lds + (bufoff) + ldsw + _i * 8192), 16, 0, 0); } } while (0)
; #define PG8_LDA(dst, b, h) do { _Pragma("unroll") for (int m = 0; m < 4; ++m) _Pragma("unroll") for (int k = 0; k < 2; ++k) dst[m][k] = *(const PG8_LAS bf16x8*)(lds + PG8_SA(b, h) + aoff + m * 2048 + k * 1024); } while (0)
; #define PG8_LDB(dst, b, h) do { _Pragma("unroll") for (int n = 0; n < 2; ++n) _Pragma("unroll") for (int k = 0; k < 2; ++k) dst[n][k] = *(const PG8_LAS bf16x8*)(lds + PG8_SB(b, h) + boff + n * 2048 + k * 1024); } while (0)
; #define PG8_WAIT_V(n) asm volatile("s_waitcnt vmcnt(" #n ")" ::: "memory")
; #define PG8_WAIT_L(n) asm volatile("s_waitcnt lgkmcnt(" #n ")" ::: "memory")
; #define PG8_BAR __builtin_amdgcn_s_barrier()
; #define PG8_SCHED __builtin_amdgcn_sched_barrier(0)
; template <class Epi, class Sched, bool ALIGN_EPI = false, bool SP2 = false, bool FP8 = false>
; __device__ __forceinline__ void gemm_phase(PG8_LAS unsigned char* lds, const Gemm g, const Sched& S, const Epi& E) {
;     ...
;             PG8_LDB(B0, 1, 0); PG8_LDB(B1, 1, 1); PG8_SCHED; PG8_LDA(At, 1, 0); PG8_STAGE(PG8_SA(0, 1), a2 + hstep, voffA);
;             PG8_WAIT_V(8); PG8_WAIT_L(0); PG8_BAR; PG8_MMA(0, 0, At, B0); PG8_MMA(0, 1, At, B1); PG8_BAR; PG8_SCHED;
;             PG8_LDA(At, 1, 1); PG8_STAGE(PG8_SB(1, 0), b3, voffB); PG8_STAGE(PG8_SB(1, 1), b3 + hstep, voffB); PG8_STAGE(PG8_SA(1, 0), a3, voffA);
;             PG8_WAIT_V(8); PG8_WAIT_L(0); PG8_BAR; PG8_MMA(1, 0, At, B0); PG8_MMA(1, 1, At, B1); PG8_BAR; PG8_SCHED;
	s_add_i32 s52, 0, 0x18000
	s_add_i32 s53, 0, 0x1c000
	s_nop 1
	v_add_u32_e32 v12, s52, v152
	v_add_u32_e32 v16, s53, v152
	ds_read_b128 v[0:3], v12
	ds_read_b128 v[4:7], v12 offset:1024
	ds_read_b128 v[8:11], v12 offset:2048
	ds_read_b128 v[12:15], v12 offset:3072
	ds_read_b128 v[134:137], v16
	ds_read_b128 v[138:141], v16 offset:1024
	ds_read_b128 v[156:159], v16 offset:2048
	ds_read_b128 v[160:163], v16 offset:3072
	s_add_u32 s0, s64, 0x18000
	v_mov_b32_e32 v64, v146
	s_mov_b32 m0, s70
	ds_read_b128 v[16:19], v153 offset:32768
	ds_read_b128 v[20:23], v153 offset:33792
	ds_read_b128 v[24:27], v153 offset:34816
	ds_read_b128 v[28:31], v153 offset:35840
	ds_read_b128 v[32:35], v153 offset:36864
	ds_read_b128 v[36:39], v153 offset:37888
	ds_read_b128 v[40:43], v153 offset:38912
	ds_read_b128 v[44:47], v153 offset:39936
	s_addc_u32 s1, s65, 0
	s_nop 0
	global_load_lds_dwordx4 v64, s[0:1]
	v_mov_b32_e32 v64, v148
	s_mov_b32 m0, s71
	s_nop 0
	global_load_lds_dwordx4 v64, s[0:1]
	s_waitcnt vmcnt(8)
	s_waitcnt lgkmcnt(0)
	s_barrier
	s_setprio 1
	v_mfma_scale_f32_16x16x128_f8f6f4 v[112:115], v[0:7], v[16:23], v[112:115], v154, v154 op_sel_hi:[0,0,0]
	v_mfma_scale_f32_16x16x128_f8f6f4 v[116:119], v[8:15], v[16:23], v[116:119], v154, v154 op_sel_hi:[0,0,0]
	v_mfma_scale_f32_16x16x128_f8f6f4 v[96:99], v[0:7], v[24:31], v[96:99], v154, v154 op_sel_hi:[0,0,0]
	v_mfma_scale_f32_16x16x128_f8f6f4 v[100:103], v[8:15], v[24:31], v[100:103], v154, v154 op_sel_hi:[0,0,0]
	v_mfma_scale_f32_16x16x128_f8f6f4 v[80:83], v[0:7], v[32:39], v[142:145], v154, v154 op_sel_hi:[0,0,0]
	v_mfma_scale_f32_16x16x128_f8f6f4 v[84:87], v[8:15], v[32:39], v[172:175], v154, v154 op_sel_hi:[0,0,0]
	v_mfma_scale_f32_16x16x128_f8f6f4 v[64:67], v[0:7], v[40:47], v[194:197], v154, v154 op_sel_hi:[0,0,0]
	v_mfma_scale_f32_16x16x128_f8f6f4 v[68:71], v[8:15], v[40:47], v[222:225], v154, v154 op_sel_hi:[0,0,0]
	s_setprio 0
	s_setprio 1
	v_mfma_scale_f32_16x16x128_f8f6f4 v[120:123], v[134:141], v[16:23], v[120:123], v154, v154 op_sel_hi:[0,0,0]
	v_mfma_scale_f32_16x16x128_f8f6f4 v[124:127], v[156:163], v[16:23], v[124:127], v154, v154 op_sel_hi:[0,0,0]
	v_mfma_scale_f32_16x16x128_f8f6f4 v[104:107], v[134:141], v[24:31], v[104:107], v154, v154 op_sel_hi:[0,0,0]
	v_mfma_scale_f32_16x16x128_f8f6f4 v[108:111], v[156:163], v[24:31], v[108:111], v154, v154 op_sel_hi:[0,0,0]
	v_mfma_scale_f32_16x16x128_f8f6f4 v[88:91], v[134:141], v[32:39], v[186:189], v154, v154 op_sel_hi:[0,0,0]
	v_mfma_scale_f32_16x16x128_f8f6f4 v[92:95], v[156:163], v[32:39], v[190:193], v154, v154 op_sel_hi:[0,0,0]
	v_mfma_scale_f32_16x16x128_f8f6f4 v[72:75], v[134:141], v[40:47], v[198:201], v154, v154 op_sel_hi:[0,0,0]
	v_mfma_scale_f32_16x16x128_f8f6f4 v[76:79], v[156:163], v[40:47], v[202:205], v154, v154 op_sel_hi:[0,0,0]
	s_setprio 0
	s_barrier
	v_mov_b32_e32 v128, v147
	ds_read_b128 v[24:27], v153 offset:49152
	ds_read_b128 v[28:31], v153 offset:50176
	ds_read_b128 v[164:167], v153 offset:51200
	ds_read_b128 v[168:171], v153 offset:52224
	ds_read_b128 v[178:181], v153 offset:53248
	ds_read_b128 v[182:185], v153 offset:54272
	ds_read_b128 v[186:189], v153 offset:55296
	ds_read_b128 v[190:193], v153 offset:56320
	s_add_i32 s0, s52, s66
	v_lshl_add_u64 v[16:17], s[62:63], 0, v[128:129]
	v_lshl_add_u64 v[16:17], v[16:17], 0, s[40:41]
	s_mov_b32 m0, s0
	v_mov_b32_e32 v128, v149
	global_load_lds_dwordx4 v[16:17], off
	s_add_i32 m0, s0, 0x2000
	v_lshl_add_u64 v[16:17], s[62:63], 0, v[128:129]
	v_lshl_add_u64 v[16:17], v[16:17], 0, s[40:41]
	s_add_u32 s0, s62, 0x18080
	global_load_lds_dwordx4 v[16:17], off
	s_addc_u32 s1, s63, 0
	v_mov_b32_e32 v16, v147
	s_add_i32 s52, s53, s66
	s_mov_b32 m0, s52
	v_mov_b32_e32 v128, v146
	global_load_lds_dwordx4 v16, s[0:1]
	v_mov_b32_e32 v16, v149
	s_add_i32 m0, s52, 0x2000
	s_nop 0
	global_load_lds_dwordx4 v16, s[0:1]
	s_mov_b32 m0, s75
	v_lshl_add_u64 v[16:17], s[64:65], 0, v[128:129]
	v_lshl_add_u64 v[16:17], v[16:17], 0, s[40:41]
	v_mov_b32_e32 v128, v148
	global_load_lds_dwordx4 v[16:17], off
	s_mov_b32 m0, s77
	v_lshl_add_u64 v[16:17], s[64:65], 0, v[128:129]
	v_lshl_add_u64 v[16:17], v[16:17], 0, s[40:41]
	global_load_lds_dwordx4 v[16:17], off
	s_waitcnt vmcnt(8)
	s_waitcnt lgkmcnt(0)
	s_barrier
	s_setprio 1
	v_mfma_scale_f32_16x16x128_f8f6f4 v[48:51], v[0:7], v[24:31], v[48:51], v154, v154 op_sel_hi:[0,0,0]
	v_mfma_scale_f32_16x16x128_f8f6f4 v[52:55], v[8:15], v[24:31], v[52:55], v154, v154 op_sel_hi:[0,0,0]
	v_mfma_scale_f32_16x16x128_f8f6f4 v[32:35], v[0:7], v[164:171], v[206:209], v154, v154 op_sel_hi:[0,0,0]
	v_mfma_scale_f32_16x16x128_f8f6f4 v[36:39], v[8:15], v[164:171], v[210:213], v154, v154 op_sel_hi:[0,0,0]
	v_mfma_scale_f32_16x16x128_f8f6f4 v[16:19], v[0:7], v[178:185], v[214:217], v154, v154 op_sel_hi:[0,0,0]
	v_mfma_scale_f32_16x16x128_f8f6f4 v[20:23], v[8:15], v[178:185], v[218:221], v154, v154 op_sel_hi:[0,0,0]
	v_mfma_scale_f32_16x16x128_f8f6f4 v[4:7], v[0:7], v[186:193], v[226:229], v154, v154 op_sel_hi:[0,0,0]
	v_mfma_scale_f32_16x16x128_f8f6f4 v[8:11], v[8:15], v[186:193], v[230:233], v154, v154 op_sel_hi:[0,0,0]
	s_setprio 0
	s_setprio 1
	v_mfma_scale_f32_16x16x128_f8f6f4 v[56:59], v[134:141], v[24:31], v[56:59], v154, v154 op_sel_hi:[0,0,0]
	v_mfma_scale_f32_16x16x128_f8f6f4 v[60:63], v[156:163], v[24:31], v[60:63], v154, v154 op_sel_hi:[0,0,0]
	v_mfma_scale_f32_16x16x128_f8f6f4 v[40:43], v[134:141], v[164:171], v[234:237], v154, v154 op_sel_hi:[0,0,0]
	v_mfma_scale_f32_16x16x128_f8f6f4 v[44:47], v[156:163], v[164:171], v[238:241], v154, v154 op_sel_hi:[0,0,0]
	v_mfma_scale_f32_16x16x128_f8f6f4 v[24:27], v[134:141], v[178:185], v[242:245], v154, v154 op_sel_hi:[0,0,0]
	v_mfma_scale_f32_16x16x128_f8f6f4 v[28:31], v[156:163], v[178:185], v[246:249], v154, v154 op_sel_hi:[0,0,0]
	v_mfma_scale_f32_16x16x128_f8f6f4 v[12:15], v[134:141], v[186:193], v[250:253], v154, v154 op_sel_hi:[0,0,0]
	v_mfma_scale_f32_16x16x128_f8f6f4 v[0:3], v[156:163], v[186:193], v[130:133], v154, v154 op_sel_hi:[0,0,0]
	s_setprio 0
	s_barrier
	s_add_i32 s91, s91, 2
	s_add_u32 s10, s10, 0x100
	s_addc_u32 s11, s11, 0
	s_add_u32 s89, s89, 0x100
	s_addc_u32 s90, s90, 0
	s_cmp_gt_u32 s91, 3
	s_cbranch_scc1 .LBB0_308

; #define PG8_STAGE(bufoff, gbase, voff) do { _Pragma("unroll") for (int _i = 0; _i < 2; ++_i) { unsigned vo_ = (voff)[_i]; if constexpr (FP8) asm volatile("" : "+v"(vo_)); \
;         __builtin_amdgcn_global_load_lds((const unsigned*)((const char*)(gbase) + vo_), (PG8_LAS unsigned*)(lds + (bufoff) + ldsw + _i * 8192), 16, 0, 0); } } while (0)
; #define PG8_LDA(dst, b, h) do { _Pragma("unroll") for (int m = 0; m < 4; ++m) _Pragma("unroll") for (int k = 0; k < 2; ++k) dst[m][k] = *(const PG8_LAS bf16x8*)(lds + PG8_SA(b, h) + aoff + m * 2048 + k * 1024); } while (0)
; #define PG8_LDB(dst, b, h) do { _Pragma("unroll") for (int n = 0; n < 2; ++n) _Pragma("unroll") for (int k = 0; k < 2; ++k) dst[n][k] = *(const PG8_LAS bf16x8*)(lds + PG8_SB(b, h) + boff + n * 2048 + k * 1024); } while (0)
; #define PG8_WAIT_V(n) asm volatile("s_waitcnt vmcnt(" #n ")" ::: "memory")
; #define PG8_WAIT_L(n) asm volatile("s_waitcnt lgkmcnt(" #n ")" ::: "memory")
; #define PG8_BAR __builtin_amdgcn_s_barrier()
; #define PG8_SCHED __builtin_amdgcn_sched_barrier(0)
; template <class Epi, class Sched, bool ALIGN_EPI = false, bool SP2 = false, bool FP8 = false>
; __device__ __forceinline__ void gemm_phase(PG8_LAS unsigned char* lds, const Gemm g, const Sched& S, const Epi& E) {
;     ...
;             PG8_LDB(B0, 0, 0); PG8_LDB(B1, 0, 1); PG8_SCHED; PG8_LDA(At, 0, 0); PG8_STAGE(PG8_SA(1, 1), a1 + hstep, voffA);
;             PG8_WAIT_V(8); PG8_WAIT_L(0); PG8_BAR; PG8_MMA(0, 0, At, B0); PG8_MMA(0, 1, At, B1); PG8_BAR; PG8_SCHED;
;             PG8_LDA(At, 0, 1); PG8_STAGE(PG8_SB(0, 0), b2, voffB); PG8_STAGE(PG8_SB(0, 1), b2 + hstep, voffB); PG8_STAGE(PG8_SA(0, 0), a2, voffA);
;             PG8_WAIT_V(8); PG8_WAIT_L(0); PG8_BAR; PG8_MMA(1, 0, At, B0); PG8_MMA(1, 1, At, B1); PG8_BAR; PG8_SCHED;
.Lmy_nobar_P4:
.LBB0_342:
	v_add_u32_e32 v140, s69, v201
	v_add_u32_e32 v156, s70, v201
	ds_read_b128 v[128:131], v140
	ds_read_b128 v[132:135], v140 offset:1024
	ds_read_b128 v[136:139], v140 offset:2048
	ds_read_b128 v[140:143], v140 offset:3072
	ds_read_b128 v[144:147], v156
	ds_read_b128 v[148:151], v156 offset:1024
	ds_read_b128 v[152:155], v156 offset:2048
	ds_read_b128 v[156:159], v156 offset:3072
	s_add_u32 s0, s10, 0xfffe0080
	s_addc_u32 s1, s11, -1
	s_cmp_eq_u32 s74, 4
	s_cselect_b32 s55, s9, s1
	s_cselect_b32 s54, s45, s0
	s_cselect_b32 s57, s43, s73
	s_cselect_b32 s56, s51, s72
	v_mov_b32_e32 v178, v197
	ds_read_b128 v[160:163], v202
	ds_read_b128 v[164:167], v202 offset:1024
	ds_read_b128 v[168:171], v202 offset:2048
	ds_read_b128 v[172:175], v202 offset:3072
	ds_read_b128 v[184:187], v202 offset:4096
	ds_read_b128 v[188:191], v202 offset:5120
	ds_read_b128 v[206:209], v202 offset:6144
	ds_read_b128 v[210:213], v202 offset:7168
	s_add_i32 m0, s53, 0xc000
	s_nop 0
	global_load_lds_dwordx4 v178, s[10:11]
	v_mov_b32_e32 v178, v199
	s_add_i32 m0, s53, 0xe000
	s_nop 0
	global_load_lds_dwordx4 v178, s[10:11]
	s_waitcnt vmcnt(8)
	s_waitcnt lgkmcnt(0)
	s_barrier
	s_setprio 1
	v_mfma_scale_f32_16x16x128_f8f6f4 v[116:119], v[128:135], v[160:167], v[116:119], v203, v203 op_sel_hi:[0,0,0]
	v_mfma_scale_f32_16x16x128_f8f6f4 v[112:115], v[136:143], v[160:167], v[112:115], v203, v203 op_sel_hi:[0,0,0]
	v_mfma_scale_f32_16x16x128_f8f6f4 v[108:111], v[128:135], v[168:175], v[108:111], v203, v203 op_sel_hi:[0,0,0]
	v_mfma_scale_f32_16x16x128_f8f6f4 v[100:103], v[136:143], v[168:175], v[100:103], v203, v203 op_sel_hi:[0,0,0]
	v_mfma_scale_f32_16x16x128_f8f6f4 v[192:195], v[128:135], v[184:191], v[92:95], v203, v203 op_sel_hi:[0,0,0]
	v_mfma_scale_f32_16x16x128_f8f6f4 v[214:217], v[136:143], v[184:191], v[84:87], v203, v203 op_sel_hi:[0,0,0]
	v_mfma_scale_f32_16x16x128_f8f6f4 v[218:221], v[128:135], v[206:213], v[76:79], v203, v203 op_sel_hi:[0,0,0]
	v_mfma_scale_f32_16x16x128_f8f6f4 v[222:225], v[136:143], v[206:213], v[68:71], v203, v203 op_sel_hi:[0,0,0]
	s_setprio 0
	s_setprio 1
	v_mfma_scale_f32_16x16x128_f8f6f4 v[124:127], v[144:151], v[160:167], v[124:127], v203, v203 op_sel_hi:[0,0,0]
	v_mfma_scale_f32_16x16x128_f8f6f4 v[120:123], v[152:159], v[160:167], v[120:123], v203, v203 op_sel_hi:[0,0,0]
	v_mfma_scale_f32_16x16x128_f8f6f4 v[104:107], v[144:151], v[168:175], v[104:107], v203, v203 op_sel_hi:[0,0,0]
	v_mfma_scale_f32_16x16x128_f8f6f4 v[96:99], v[152:159], v[168:175], v[96:99], v203, v203 op_sel_hi:[0,0,0]
	v_mfma_scale_f32_16x16x128_f8f6f4 v[160:163], v[144:151], v[184:191], v[88:91], v203, v203 op_sel_hi:[0,0,0]
	v_mfma_scale_f32_16x16x128_f8f6f4 v[164:167], v[152:159], v[184:191], v[80:83], v203, v203 op_sel_hi:[0,0,0]
	v_mfma_scale_f32_16x16x128_f8f6f4 v[168:171], v[144:151], v[206:213], v[72:75], v203, v203 op_sel_hi:[0,0,0]
	v_mfma_scale_f32_16x16x128_f8f6f4 v[172:175], v[152:159], v[206:213], v[64:67], v203, v203 op_sel_hi:[0,0,0]
	s_setprio 0
	s_barrier
	v_mov_b32_e32 v178, v198
	s_add_i32 s0, s69, s41
	s_nop 2
	ds_read_b128 v[64:67], v202 offset:16384
	ds_read_b128 v[68:71], v202 offset:17408
	ds_read_b128 v[72:75], v202 offset:18432
	ds_read_b128 v[76:79], v202 offset:19456
	ds_read_b128 v[80:83], v202 offset:20480
	ds_read_b128 v[84:87], v202 offset:21504
	ds_read_b128 v[88:91], v202 offset:22528
	ds_read_b128 v[92:95], v202 offset:23552
	s_mov_b32 m0, s0
	s_nop 0
	global_load_lds_dwordx4 v178, s[56:57]
	v_mov_b32_e32 v178, v200
	s_add_i32 m0, s0, 0x2000
	s_add_u32 s0, s56, 0x20000
	global_load_lds_dwordx4 v178, s[56:57]
	s_addc_u32 s1, s57, 0
	v_mov_b32_e32 v178, v198
	s_add_i32 s75, s70, s41
	s_mov_b32 m0, s75
	s_nop 0
	global_load_lds_dwordx4 v178, s[0:1]
	v_mov_b32_e32 v178, v200
	s_add_i32 m0, s75, 0x2000
	s_nop 0
	global_load_lds_dwordx4 v178, s[0:1]
	v_mov_b32_e32 v178, v197
	s_mov_b32 m0, s53
	s_nop 0
	global_load_lds_dwordx4 v178, s[54:55]
	v_mov_b32_e32 v178, v199
	s_mov_b32 m0, s58
	s_nop 0
	global_load_lds_dwordx4 v178, s[54:55]
	s_waitcnt vmcnt(8)
	s_waitcnt lgkmcnt(0)
	s_barrier
	s_setprio 1
	v_mfma_scale_f32_16x16x128_f8f6f4 v[52:55], v[128:135], v[64:71], v[52:55], v203, v203 op_sel_hi:[0,0,0]
	v_mfma_scale_f32_16x16x128_f8f6f4 v[48:51], v[136:143], v[64:71], v[48:51], v203, v203 op_sel_hi:[0,0,0]
	v_mfma_scale_f32_16x16x128_f8f6f4 v[44:47], v[128:135], v[72:79], v[44:47], v203, v203 op_sel_hi:[0,0,0]
	v_mfma_scale_f32_16x16x128_f8f6f4 v[184:187], v[136:143], v[72:79], v[36:39], v203, v203 op_sel_hi:[0,0,0]
	v_mfma_scale_f32_16x16x128_f8f6f4 v[188:191], v[128:135], v[80:87], v[28:31], v203, v203 op_sel_hi:[0,0,0]
	v_mfma_scale_f32_16x16x128_f8f6f4 v[206:209], v[136:143], v[80:87], v[20:23], v203, v203 op_sel_hi:[0,0,0]
	v_mfma_scale_f32_16x16x128_f8f6f4 v[210:213], v[128:135], v[88:95], v[12:15], v203, v203 op_sel_hi:[0,0,0]
	v_mfma_scale_f32_16x16x128_f8f6f4 v[226:229], v[136:143], v[88:95], v[4:7], v203, v203 op_sel_hi:[0,0,0]
	s_setprio 0
	s_setprio 1
	v_mfma_scale_f32_16x16x128_f8f6f4 v[40:43], v[144:151], v[72:79], v[40:43], v203, v203 op_sel_hi:[0,0,0]
	v_mfma_scale_f32_16x16x128_f8f6f4 v[230:233], v[144:151], v[64:71], v[60:63], v203, v203 op_sel_hi:[0,0,0]
	v_mfma_scale_f32_16x16x128_f8f6f4 v[234:237], v[152:159], v[64:71], v[56:59], v203, v203 op_sel_hi:[0,0,0]
	v_mfma_scale_f32_16x16x128_f8f6f4 v[238:241], v[152:159], v[72:79], v[32:35], v203, v203 op_sel_hi:[0,0,0]
	v_mfma_scale_f32_16x16x128_f8f6f4 v[242:245], v[144:151], v[80:87], v[24:27], v203, v203 op_sel_hi:[0,0,0]
	v_mfma_scale_f32_16x16x128_f8f6f4 v[246:249], v[152:159], v[80:87], v[16:19], v203, v203 op_sel_hi:[0,0,0]
	v_mfma_scale_f32_16x16x128_f8f6f4 v[250:253], v[144:151], v[88:95], v[8:11], v203, v203 op_sel_hi:[0,0,0]
	v_mfma_scale_f32_16x16x128_f8f6f4 v[180:183], v[152:159], v[88:95], v[0:3], v203, v203 op_sel_hi:[0,0,0]
	s_setprio 0
	s_barrier
; #define PG8_STAGE(bufoff, gbase, voff) do { _Pragma("unroll") for (int _i = 0; _i < 2; ++_i) { unsigned vo_ = (voff)[_i]; if constexpr (FP8) asm volatile("" : "+v"(vo_)); \
;         __builtin_amdgcn_global_load_lds((const unsigned*)((const char*)(gbase) + vo_), (PG8_LAS unsigned*)(lds + (bufoff) + ldsw + _i * 8192), 16, 0, 0); } } while (0)
; #define PG8_LDA(dst, b, h) do { _Pragma("unroll") for (int m = 0; m < 4; ++m) _Pragma("unroll") for (int k = 0; k < 2; ++k) dst[m][k] = *(const PG8_LAS bf16x8*)(lds + PG8_SA(b, h) + aoff + m * 2048 + k * 1024); } while (0)
; #define PG8_LDB(dst, b, h) do { _Pragma("unroll") for (int n = 0; n < 2; ++n) _Pragma("unroll") for (int k = 0; k < 2; ++k) dst[n][k] = *(const PG8_LAS bf16x8*)(lds + PG8_SB(b, h) + boff + n * 2048 + k * 1024); } while (0)
; #define PG8_WAIT_V(n) asm volatile("s_waitcnt vmcnt(" #n ")" ::: "memory")
; #define PG8_WAIT_L(n) asm volatile("s_waitcnt lgkmcnt(" #n ")" ::: "memory")
; #define PG8_BAR __builtin_amdgcn_s_barrier()
; #define PG8_SCHED __builtin_amdgcn_sched_barrier(0)
; template <class Epi, class Sched, bool ALIGN_EPI = false, bool SP2 = false, bool FP8 = false>
; __device__ __forceinline__ void gemm_phase(PG8_LAS unsigned char* lds, const Gemm g, const Sched& S, const Epi& E) {
;     ...
;             PG8_LDB(B0, 1, 0); PG8_LDB(B1, 1, 1); PG8_SCHED; PG8_LDA(At, 1, 0); PG8_STAGE(PG8_SA(0, 1), a2 + hstep, voffA);
;             PG8_WAIT_V(8); PG8_WAIT_L(0); PG8_BAR; PG8_MMA(0, 0, At, B0); PG8_MMA(0, 1, At, B1); PG8_BAR; PG8_SCHED;
;             PG8_LDA(At, 1, 1); PG8_STAGE(PG8_SB(1, 0), b3, voffB); PG8_STAGE(PG8_SB(1, 1), b3 + hstep, voffB); PG8_STAGE(PG8_SA(1, 0), a3, voffA);
;             PG8_WAIT_V(8); PG8_WAIT_L(0); PG8_BAR; PG8_MMA(1, 0, At, B0); PG8_MMA(1, 1, At, B1); PG8_BAR; PG8_SCHED;
	s_add_i32 s75, 0, 0x18000
	s_nop 2
	v_add_u32_e32 v8, s75, v201
	s_add_i32 s77, 0, 0x1c000
	ds_read_b128 v[0:3], v8
	ds_read_b128 v[4:7], v8 offset:1024
	ds_read_b128 v[56:59], v8 offset:2048
	ds_read_b128 v[60:63], v8 offset:3072
	v_add_u32_e32 v8, s77, v201
	ds_read_b128 v[128:131], v8
	ds_read_b128 v[132:135], v8 offset:1024
	ds_read_b128 v[136:139], v8 offset:2048
	ds_read_b128 v[140:143], v8 offset:3072
	s_add_u32 s0, s54, 0x20000
	v_mov_b32_e32 v64, v197
	s_mov_b32 m0, s59
	ds_read_b128 v[8:11], v202 offset:32768
	ds_read_b128 v[12:15], v202 offset:33792
	ds_read_b128 v[16:19], v202 offset:34816
	ds_read_b128 v[20:23], v202 offset:35840
	ds_read_b128 v[24:27], v202 offset:36864
	ds_read_b128 v[28:31], v202 offset:37888
	ds_read_b128 v[32:35], v202 offset:38912
	ds_read_b128 v[36:39], v202 offset:39936
	s_addc_u32 s1, s55, 0
	s_nop 0
	global_load_lds_dwordx4 v64, s[0:1]
	v_mov_b32_e32 v64, v199
	s_mov_b32 m0, s60
	s_nop 0
	global_load_lds_dwordx4 v64, s[0:1]
	s_waitcnt vmcnt(8)
	s_waitcnt lgkmcnt(0)
	s_barrier
	s_setprio 1
	v_mfma_scale_f32_16x16x128_f8f6f4 v[116:119], v[0:7], v[8:15], v[116:119], v203, v203 op_sel_hi:[0,0,0]
	v_mfma_scale_f32_16x16x128_f8f6f4 v[112:115], v[56:63], v[8:15], v[112:115], v203, v203 op_sel_hi:[0,0,0]
	v_mfma_scale_f32_16x16x128_f8f6f4 v[108:111], v[0:7], v[16:23], v[108:111], v203, v203 op_sel_hi:[0,0,0]
	v_mfma_scale_f32_16x16x128_f8f6f4 v[100:103], v[56:63], v[16:23], v[100:103], v203, v203 op_sel_hi:[0,0,0]
	v_mfma_scale_f32_16x16x128_f8f6f4 v[92:95], v[0:7], v[24:31], v[192:195], v203, v203 op_sel_hi:[0,0,0]
	v_mfma_scale_f32_16x16x128_f8f6f4 v[84:87], v[56:63], v[24:31], v[214:217], v203, v203 op_sel_hi:[0,0,0]
	v_mfma_scale_f32_16x16x128_f8f6f4 v[76:79], v[0:7], v[32:39], v[218:221], v203, v203 op_sel_hi:[0,0,0]
	v_mfma_scale_f32_16x16x128_f8f6f4 v[68:71], v[56:63], v[32:39], v[222:225], v203, v203 op_sel_hi:[0,0,0]
	s_setprio 0
	s_setprio 1
	v_mfma_scale_f32_16x16x128_f8f6f4 v[124:127], v[128:135], v[8:15], v[124:127], v203, v203 op_sel_hi:[0,0,0]
	v_mfma_scale_f32_16x16x128_f8f6f4 v[120:123], v[136:143], v[8:15], v[120:123], v203, v203 op_sel_hi:[0,0,0]
	v_mfma_scale_f32_16x16x128_f8f6f4 v[104:107], v[128:135], v[16:23], v[104:107], v203, v203 op_sel_hi:[0,0,0]
	v_mfma_scale_f32_16x16x128_f8f6f4 v[96:99], v[136:143], v[16:23], v[96:99], v203, v203 op_sel_hi:[0,0,0]
	v_mfma_scale_f32_16x16x128_f8f6f4 v[88:91], v[128:135], v[24:31], v[160:163], v203, v203 op_sel_hi:[0,0,0]
	v_mfma_scale_f32_16x16x128_f8f6f4 v[80:83], v[136:143], v[24:31], v[164:167], v203, v203 op_sel_hi:[0,0,0]
	v_mfma_scale_f32_16x16x128_f8f6f4 v[72:75], v[128:135], v[32:39], v[168:171], v203, v203 op_sel_hi:[0,0,0]
	v_mfma_scale_f32_16x16x128_f8f6f4 v[64:67], v[136:143], v[32:39], v[172:175], v203, v203 op_sel_hi:[0,0,0]
	s_setprio 0
	s_barrier
	v_mov_b32_e32 v178, v198
	ds_read_b128 v[144:147], v202 offset:49152
	ds_read_b128 v[148:151], v202 offset:50176
	ds_read_b128 v[152:155], v202 offset:51200
	ds_read_b128 v[156:159], v202 offset:52224
	ds_read_b128 v[160:163], v202 offset:53248
	ds_read_b128 v[164:167], v202 offset:54272
	ds_read_b128 v[168:171], v202 offset:55296
	ds_read_b128 v[172:175], v202 offset:56320
	s_add_i32 s0, s75, s41
	v_lshl_add_u64 v[8:9], s[56:57], 0, v[178:179]
	v_lshl_add_u64 v[8:9], v[8:9], 0, s[14:15]
	s_mov_b32 m0, s0
	v_mov_b32_e32 v178, v200
	global_load_lds_dwordx4 v[8:9], off
	s_add_i32 m0, s0, 0x2000
	v_lshl_add_u64 v[8:9], s[56:57], 0, v[178:179]
	v_lshl_add_u64 v[8:9], v[8:9], 0, s[14:15]
	s_add_u32 s0, s56, 0x20080
	global_load_lds_dwordx4 v[8:9], off
	s_addc_u32 s1, s57, 0
	v_mov_b32_e32 v8, v198
	s_add_i32 s56, s77, s41
	s_mov_b32 m0, s56
	v_mov_b32_e32 v178, v197
	global_load_lds_dwordx4 v8, s[0:1]
	v_mov_b32_e32 v8, v200
	s_add_i32 m0, s56, 0x2000
	s_nop 0
	global_load_lds_dwordx4 v8, s[0:1]
	s_mov_b32 m0, s66
	v_lshl_add_u64 v[8:9], s[54:55], 0, v[178:179]
	v_lshl_add_u64 v[8:9], v[8:9], 0, s[14:15]
	v_mov_b32_e32 v178, v199
	global_load_lds_dwordx4 v[8:9], off
	s_mov_b32 m0, s67
	v_lshl_add_u64 v[8:9], s[54:55], 0, v[178:179]
	v_lshl_add_u64 v[8:9], v[8:9], 0, s[14:15]
	global_load_lds_dwordx4 v[8:9], off
	s_waitcnt vmcnt(8)
	s_waitcnt lgkmcnt(0)
	s_barrier
	s_setprio 1
	v_mfma_scale_f32_16x16x128_f8f6f4 v[52:55], v[0:7], v[144:151], v[52:55], v203, v203 op_sel_hi:[0,0,0]
	v_mfma_scale_f32_16x16x128_f8f6f4 v[48:51], v[56:63], v[144:151], v[48:51], v203, v203 op_sel_hi:[0,0,0]
	v_mfma_scale_f32_16x16x128_f8f6f4 v[44:47], v[0:7], v[152:159], v[44:47], v203, v203 op_sel_hi:[0,0,0]
	v_mfma_scale_f32_16x16x128_f8f6f4 v[36:39], v[56:63], v[152:159], v[184:187], v203, v203 op_sel_hi:[0,0,0]
	v_mfma_scale_f32_16x16x128_f8f6f4 v[28:31], v[0:7], v[160:167], v[188:191], v203, v203 op_sel_hi:[0,0,0]
	v_mfma_scale_f32_16x16x128_f8f6f4 v[20:23], v[56:63], v[160:167], v[206:209], v203, v203 op_sel_hi:[0,0,0]
	v_mfma_scale_f32_16x16x128_f8f6f4 v[12:15], v[0:7], v[168:175], v[210:213], v203, v203 op_sel_hi:[0,0,0]
	v_mfma_scale_f32_16x16x128_f8f6f4 v[4:7], v[56:63], v[168:175], v[226:229], v203, v203 op_sel_hi:[0,0,0]
	s_setprio 0
	s_setprio 1
	v_mfma_scale_f32_16x16x128_f8f6f4 v[60:63], v[128:135], v[144:151], v[230:233], v203, v203 op_sel_hi:[0,0,0]
	v_mfma_scale_f32_16x16x128_f8f6f4 v[56:59], v[136:143], v[144:151], v[234:237], v203, v203 op_sel_hi:[0,0,0]
	v_mfma_scale_f32_16x16x128_f8f6f4 v[40:43], v[128:135], v[152:159], v[40:43], v203, v203 op_sel_hi:[0,0,0]
	v_mfma_scale_f32_16x16x128_f8f6f4 v[32:35], v[136:143], v[152:159], v[238:241], v203, v203 op_sel_hi:[0,0,0]
	v_mfma_scale_f32_16x16x128_f8f6f4 v[24:27], v[128:135], v[160:167], v[242:245], v203, v203 op_sel_hi:[0,0,0]
	v_mfma_scale_f32_16x16x128_f8f6f4 v[16:19], v[136:143], v[160:167], v[246:249], v203, v203 op_sel_hi:[0,0,0]
	v_mfma_scale_f32_16x16x128_f8f6f4 v[8:11], v[128:135], v[168:175], v[250:253], v203, v203 op_sel_hi:[0,0,0]
	v_mfma_scale_f32_16x16x128_f8f6f4 v[0:3], v[136:143], v[168:175], v[180:183], v203, v203 op_sel_hi:[0,0,0]
	s_setprio 0
	s_barrier
	s_add_i32 s74, s74, 2
	s_add_u32 s10, s10, 0x100
	s_addc_u32 s11, s11, 0
	s_add_u32 s72, s72, 0x100
	s_addc_u32 s73, s73, 0
	s_cmp_gt_u32 s74, 5
	s_cbranch_scc0 .LBB0_342
	s_and_b64 vcc, exec, s[38:39]
	s_cbranch_vccz .LBB0_345

; #define PG8_STAGE(bufoff, gbase, voff) do { _Pragma("unroll") for (int _i = 0; _i < 2; ++_i) { unsigned vo_ = (voff)[_i]; if constexpr (FP8) asm volatile("" : "+v"(vo_)); \
;         __builtin_amdgcn_global_load_lds((const unsigned*)((const char*)(gbase) + vo_), (PG8_LAS unsigned*)(lds + (bufoff) + ldsw + _i * 8192), 16, 0, 0); } } while (0)
; #define PG8_LDA(dst, b, h) do { _Pragma("unroll") for (int m = 0; m < 4; ++m) _Pragma("unroll") for (int k = 0; k < 2; ++k) dst[m][k] = *(const PG8_LAS bf16x8*)(lds + PG8_SA(b, h) + aoff + m * 2048 + k * 1024); } while (0)
; #define PG8_LDB(dst, b, h) do { _Pragma("unroll") for (int n = 0; n < 2; ++n) _Pragma("unroll") for (int k = 0; k < 2; ++k) dst[n][k] = *(const PG8_LAS bf16x8*)(lds + PG8_SB(b, h) + boff + n * 2048 + k * 1024); } while (0)
; #define PG8_WAIT_V(n) asm volatile("s_waitcnt vmcnt(" #n ")" ::: "memory")
; #define PG8_WAIT_L(n) asm volatile("s_waitcnt lgkmcnt(" #n ")" ::: "memory")
; #define PG8_BAR __builtin_amdgcn_s_barrier()
; #define PG8_SCHED __builtin_amdgcn_sched_barrier(0)
; template <class Epi, class Sched, bool ALIGN_EPI = false, bool SP2 = false, bool FP8 = false>
; __device__ __forceinline__ void gemm_phase(PG8_LAS unsigned char* lds, const Gemm g, const Sched& S, const Epi& E) {
;     ...
;             PG8_LDB(B0, 0, 0); PG8_LDB(B1, 0, 1); PG8_SCHED; PG8_LDA(At, 0, 0); PG8_STAGE(PG8_SA(1, 1), a1 + hstep, voffA);
;             PG8_WAIT_V(8); PG8_WAIT_L(0); PG8_BAR; PG8_MMA(0, 0, At, B0); PG8_MMA(0, 1, At, B1); PG8_BAR; PG8_SCHED;
;             PG8_LDA(At, 0, 1); PG8_STAGE(PG8_SB(0, 0), b2, voffB); PG8_STAGE(PG8_SB(0, 1), b2 + hstep, voffB); PG8_STAGE(PG8_SA(0, 0), a2, voffA);
;             PG8_WAIT_V(8); PG8_WAIT_L(0); PG8_BAR; PG8_MMA(1, 0, At, B0); PG8_MMA(1, 1, At, B1); PG8_BAR; PG8_SCHED;
.Lmy_nobar_P5:
.LBB0_391:
	ds_read_b128 v[146:149], v153
	ds_read_b128 v[158:161], v153 offset:1024
	ds_read_b128 v[162:165], v153 offset:2048
	ds_read_b128 v[166:169], v153 offset:3072
	ds_read_b128 v[170:173], v154
	ds_read_b128 v[174:177], v154 offset:1024
	ds_read_b128 v[178:181], v154 offset:2048
	ds_read_b128 v[182:185], v154 offset:3072
	s_add_u32 s0, s40, 0xfffc0080
	s_addc_u32 s1, s41, -1
	s_cmp_eq_u32 s61, 12
	s_cselect_b32 s45, s15, s1
	s_cselect_b32 s44, s57, s0
	s_cselect_b32 s43, s13, s60
	s_cselect_b32 s42, s58, s59
	v_lshl_add_u64 v[218:219], s[40:41], 0, v[138:139]
	s_add_i32 m0, s39, 0xc000
	ds_read_b128 v[186:189], v155
	ds_read_b128 v[190:193], v155 offset:1024
	ds_read_b128 v[194:197], v155 offset:2048
	ds_read_b128 v[198:201], v155 offset:3072
	ds_read_b128 v[202:205], v155 offset:4096
	ds_read_b128 v[206:209], v155 offset:5120
	ds_read_b128 v[210:213], v155 offset:6144
	ds_read_b128 v[214:217], v155 offset:7168
	global_load_lds_dwordx4 v[218:219], off
	v_lshl_add_u64 v[218:219], s[40:41], 0, v[140:141]
	s_add_i32 m0, s39, 0xe000
	s_nop 0
	global_load_lds_dwordx4 v[218:219], off
	s_waitcnt vmcnt(8)
	s_waitcnt lgkmcnt(0)
	s_barrier
	s_setprio 1
	v_mfma_f32_16x16x32_bf16 v[124:127], v[146:149], v[186:189], v[124:127]
	v_mfma_f32_16x16x32_bf16 v[120:123], v[162:165], v[186:189], v[120:123]
	v_mfma_f32_16x16x32_bf16 v[108:111], v[146:149], v[194:197], v[108:111]
	v_mfma_f32_16x16x32_bf16 v[104:107], v[162:165], v[194:197], v[104:107]
	v_mfma_f32_16x16x32_bf16 v[92:95], v[146:149], v[202:205], v[92:95]
	v_mfma_f32_16x16x32_bf16 v[88:91], v[162:165], v[202:205], v[88:91]
	v_mfma_f32_16x16x32_bf16 v[76:79], v[146:149], v[210:213], v[76:79]
	v_mfma_f32_16x16x32_bf16 v[72:75], v[162:165], v[210:213], v[72:75]
	v_mfma_f32_16x16x32_bf16 v[124:127], v[158:161], v[190:193], v[124:127]
	v_mfma_f32_16x16x32_bf16 v[120:123], v[166:169], v[190:193], v[120:123]
	v_mfma_f32_16x16x32_bf16 v[108:111], v[158:161], v[198:201], v[108:111]
	v_mfma_f32_16x16x32_bf16 v[104:107], v[166:169], v[198:201], v[104:107]
	v_mfma_f32_16x16x32_bf16 v[92:95], v[158:161], v[206:209], v[92:95]
	v_mfma_f32_16x16x32_bf16 v[88:91], v[166:169], v[206:209], v[88:91]
	v_mfma_f32_16x16x32_bf16 v[76:79], v[158:161], v[214:217], v[76:79]
	v_mfma_f32_16x16x32_bf16 v[72:75], v[166:169], v[214:217], v[72:75]
	s_setprio 0
	s_setprio 1
	v_mfma_f32_16x16x32_bf16 v[116:119], v[170:173], v[186:189], v[116:119]
	v_mfma_f32_16x16x32_bf16 v[112:115], v[178:181], v[186:189], v[112:115]
	v_mfma_f32_16x16x32_bf16 v[100:103], v[170:173], v[194:197], v[100:103]
	v_mfma_f32_16x16x32_bf16 v[96:99], v[178:181], v[194:197], v[96:99]
	v_mfma_f32_16x16x32_bf16 v[84:87], v[170:173], v[202:205], v[84:87]
	v_mfma_f32_16x16x32_bf16 v[80:83], v[178:181], v[202:205], v[80:83]
	v_mfma_f32_16x16x32_bf16 v[68:71], v[170:173], v[210:213], v[68:71]
	v_mfma_f32_16x16x32_bf16 v[64:67], v[178:181], v[210:213], v[64:67]
	v_mfma_f32_16x16x32_bf16 v[116:119], v[174:177], v[190:193], v[116:119]
	v_mfma_f32_16x16x32_bf16 v[112:115], v[182:185], v[190:193], v[112:115]
	v_mfma_f32_16x16x32_bf16 v[100:103], v[174:177], v[198:201], v[100:103]
	v_mfma_f32_16x16x32_bf16 v[96:99], v[182:185], v[198:201], v[96:99]
	v_mfma_f32_16x16x32_bf16 v[84:87], v[174:177], v[206:209], v[84:87]
	v_mfma_f32_16x16x32_bf16 v[80:83], v[182:185], v[206:209], v[80:83]
	v_mfma_f32_16x16x32_bf16 v[68:71], v[174:177], v[214:217], v[68:71]
	v_mfma_f32_16x16x32_bf16 v[64:67], v[182:185], v[214:217], v[64:67]
	s_setprio 0
	s_barrier
	s_add_i32 s0, s54, s46
	v_lshl_add_u64 v[218:219], s[42:43], 0, v[132:133]
	s_mov_b32 m0, s0
	ds_read_b128 v[186:189], v155 offset:16384
	ds_read_b128 v[190:193], v155 offset:17408
	ds_read_b128 v[194:197], v155 offset:18432
	ds_read_b128 v[198:201], v155 offset:19456
	ds_read_b128 v[202:205], v155 offset:20480
	ds_read_b128 v[206:209], v155 offset:21504
	ds_read_b128 v[210:213], v155 offset:22528
	ds_read_b128 v[214:217], v155 offset:23552
	global_load_lds_dwordx4 v[218:219], off
	s_add_i32 m0, s0, 0x2000
	s_add_u32 s0, s42, 0x40000
	v_lshl_add_u64 v[220:221], s[42:43], 0, v[128:129]
	s_addc_u32 s1, s43, 0
	s_add_i32 s62, s55, s46
	global_load_lds_dwordx4 v[220:221], off
	v_lshl_add_u64 v[222:223], s[0:1], 0, v[132:133]
	s_mov_b32 m0, s62
	v_lshl_add_u64 v[224:225], s[44:45], 0, v[130:131]
	global_load_lds_dwordx4 v[222:223], off
	v_lshl_add_u64 v[222:223], s[0:1], 0, v[128:129]
	s_add_i32 m0, s62, 0x2000
	s_nop 0
	global_load_lds_dwordx4 v[222:223], off
	v_lshl_add_u64 v[222:223], s[44:45], 0, v[134:135]
	s_mov_b32 m0, s39
	s_nop 0
	global_load_lds_dwordx4 v[222:223], off
	s_mov_b32 m0, s48
	s_nop 0
	global_load_lds_dwordx4 v[224:225], off
	s_waitcnt vmcnt(8)
	s_waitcnt lgkmcnt(0)
	s_barrier
; #define PG8_STAGE(bufoff, gbase, voff) do { _Pragma("unroll") for (int _i = 0; _i < 2; ++_i) { unsigned vo_ = (voff)[_i]; if constexpr (FP8) asm volatile("" : "+v"(vo_)); \
;         __builtin_amdgcn_global_load_lds((const unsigned*)((const char*)(gbase) + vo_), (PG8_LAS unsigned*)(lds + (bufoff) + ldsw + _i * 8192), 16, 0, 0); } } while (0)
; #define PG8_LDA(dst, b, h) do { _Pragma("unroll") for (int m = 0; m < 4; ++m) _Pragma("unroll") for (int k = 0; k < 2; ++k) dst[m][k] = *(const PG8_LAS bf16x8*)(lds + PG8_SA(b, h) + aoff + m * 2048 + k * 1024); } while (0)
; #define PG8_LDB(dst, b, h) do { _Pragma("unroll") for (int n = 0; n < 2; ++n) _Pragma("unroll") for (int k = 0; k < 2; ++k) dst[n][k] = *(const PG8_LAS bf16x8*)(lds + PG8_SB(b, h) + boff + n * 2048 + k * 1024); } while (0)
; #define PG8_WAIT_V(n) asm volatile("s_waitcnt vmcnt(" #n ")" ::: "memory")
; #define PG8_WAIT_L(n) asm volatile("s_waitcnt lgkmcnt(" #n ")" ::: "memory")
; #define PG8_BAR __builtin_amdgcn_s_barrier()
; #define PG8_SCHED __builtin_amdgcn_sched_barrier(0)
; template <class Epi, class Sched, bool ALIGN_EPI = false, bool SP2 = false, bool FP8 = false>
; __device__ __forceinline__ void gemm_phase(PG8_LAS unsigned char* lds, const Gemm g, const Sched& S, const Epi& E) {
;     ...
;             PG8_WAIT_V(8); PG8_WAIT_L(0); PG8_BAR; PG8_MMA(1, 0, At, B0); PG8_MMA(1, 1, At, B1); PG8_BAR; PG8_SCHED;
;             PG8_LDB(B0, 1, 0); PG8_LDB(B1, 1, 1); PG8_SCHED; PG8_LDA(At, 1, 0); PG8_STAGE(PG8_SA(0, 1), a2 + hstep, voffA);
;             PG8_WAIT_V(8); PG8_WAIT_L(0); PG8_BAR; PG8_MMA(0, 0, At, B0); PG8_MMA(0, 1, At, B1); PG8_BAR; PG8_SCHED;
;             PG8_LDA(At, 1, 1); PG8_STAGE(PG8_SB(1, 0), b3, voffB); PG8_STAGE(PG8_SB(1, 1), b3 + hstep, voffB); PG8_STAGE(PG8_SA(1, 0), a3, voffA);
	s_setprio 1
	v_mfma_f32_16x16x32_bf16 v[60:63], v[146:149], v[186:189], v[60:63]
	v_mfma_f32_16x16x32_bf16 v[56:59], v[162:165], v[186:189], v[56:59]
	v_mfma_f32_16x16x32_bf16 v[44:47], v[146:149], v[194:197], v[44:47]
	v_mfma_f32_16x16x32_bf16 v[40:43], v[162:165], v[194:197], v[40:43]
	v_mfma_f32_16x16x32_bf16 v[28:31], v[146:149], v[202:205], v[28:31]
	v_mfma_f32_16x16x32_bf16 v[24:27], v[162:165], v[202:205], v[24:27]
	v_mfma_f32_16x16x32_bf16 v[12:15], v[146:149], v[210:213], v[12:15]
	v_mfma_f32_16x16x32_bf16 v[8:11], v[162:165], v[210:213], v[8:11]
	v_mfma_f32_16x16x32_bf16 v[60:63], v[158:161], v[190:193], v[60:63]
	v_mfma_f32_16x16x32_bf16 v[56:59], v[166:169], v[190:193], v[56:59]
	v_mfma_f32_16x16x32_bf16 v[44:47], v[158:161], v[198:201], v[44:47]
	v_mfma_f32_16x16x32_bf16 v[40:43], v[166:169], v[198:201], v[40:43]
	v_mfma_f32_16x16x32_bf16 v[28:31], v[158:161], v[206:209], v[28:31]
	v_mfma_f32_16x16x32_bf16 v[24:27], v[166:169], v[206:209], v[24:27]
	v_mfma_f32_16x16x32_bf16 v[12:15], v[158:161], v[214:217], v[12:15]
	v_mfma_f32_16x16x32_bf16 v[8:11], v[166:169], v[214:217], v[8:11]
	s_setprio 0
	s_setprio 1
	v_mfma_f32_16x16x32_bf16 v[52:55], v[170:173], v[186:189], v[52:55]
	v_mfma_f32_16x16x32_bf16 v[48:51], v[178:181], v[186:189], v[48:51]
	v_mfma_f32_16x16x32_bf16 v[36:39], v[170:173], v[194:197], v[36:39]
	v_mfma_f32_16x16x32_bf16 v[32:35], v[178:181], v[194:197], v[32:35]
	v_mfma_f32_16x16x32_bf16 v[20:23], v[170:173], v[202:205], v[20:23]
	v_mfma_f32_16x16x32_bf16 v[16:19], v[178:181], v[202:205], v[16:19]
	v_mfma_f32_16x16x32_bf16 v[4:7], v[170:173], v[210:213], v[4:7]
	v_mfma_f32_16x16x32_bf16 v[0:3], v[178:181], v[210:213], v[0:3]
	v_mfma_f32_16x16x32_bf16 v[52:55], v[174:177], v[190:193], v[52:55]
	v_mfma_f32_16x16x32_bf16 v[48:51], v[182:185], v[190:193], v[48:51]
	v_mfma_f32_16x16x32_bf16 v[36:39], v[174:177], v[198:201], v[36:39]
	v_mfma_f32_16x16x32_bf16 v[32:35], v[182:185], v[198:201], v[32:35]
	v_mfma_f32_16x16x32_bf16 v[20:23], v[174:177], v[206:209], v[20:23]
	v_mfma_f32_16x16x32_bf16 v[16:19], v[182:185], v[206:209], v[16:19]
	v_mfma_f32_16x16x32_bf16 v[4:7], v[174:177], v[214:217], v[4:7]
	v_mfma_f32_16x16x32_bf16 v[0:3], v[182:185], v[214:217], v[0:3]
	s_setprio 0
	s_barrier
	s_add_i32 s62, 0, 0x18000
	s_add_i32 s63, 0, 0x1c000
	v_add_u32_e32 v166, s62, v151
	v_add_u32_e32 v182, s63, v151
	ds_read_b128 v[146:149], v166
	ds_read_b128 v[158:161], v166 offset:1024
	ds_read_b128 v[162:165], v166 offset:2048
	ds_read_b128 v[166:169], v166 offset:3072
	ds_read_b128 v[170:173], v182
	ds_read_b128 v[174:177], v182 offset:1024
	ds_read_b128 v[178:181], v182 offset:2048
	ds_read_b128 v[182:185], v182 offset:3072
	s_add_u32 s0, s44, 0x40000
	s_addc_u32 s1, s45, 0
	s_mov_b32 m0, s49
	v_lshl_add_u64 v[226:227], s[0:1], 0, v[134:135]
	ds_read_b128 v[186:189], v155 offset:32768
	ds_read_b128 v[190:193], v155 offset:33792
	ds_read_b128 v[194:197], v155 offset:34816
	ds_read_b128 v[198:201], v155 offset:35840
	ds_read_b128 v[202:205], v155 offset:36864
	ds_read_b128 v[206:209], v155 offset:37888
	ds_read_b128 v[210:213], v155 offset:38912
	ds_read_b128 v[214:217], v155 offset:39936
	global_load_lds_dwordx4 v[226:227], off
	v_lshl_add_u64 v[226:227], s[0:1], 0, v[130:131]
	s_mov_b32 m0, s50
	s_nop 0
	global_load_lds_dwordx4 v[226:227], off
	s_waitcnt vmcnt(8)
	s_waitcnt lgkmcnt(0)
	s_barrier
	s_setprio 1
	v_mfma_f32_16x16x32_bf16 v[124:127], v[146:149], v[186:189], v[124:127]
	v_mfma_f32_16x16x32_bf16 v[120:123], v[162:165], v[186:189], v[120:123]
	v_mfma_f32_16x16x32_bf16 v[108:111], v[146:149], v[194:197], v[108:111]
	v_mfma_f32_16x16x32_bf16 v[104:107], v[162:165], v[194:197], v[104:107]
	v_mfma_f32_16x16x32_bf16 v[92:95], v[146:149], v[202:205], v[92:95]
	v_mfma_f32_16x16x32_bf16 v[88:91], v[162:165], v[202:205], v[88:91]
	v_mfma_f32_16x16x32_bf16 v[76:79], v[146:149], v[210:213], v[76:79]
	v_mfma_f32_16x16x32_bf16 v[72:75], v[162:165], v[210:213], v[72:75]
	v_mfma_f32_16x16x32_bf16 v[124:127], v[158:161], v[190:193], v[124:127]
	v_mfma_f32_16x16x32_bf16 v[120:123], v[166:169], v[190:193], v[120:123]
	v_mfma_f32_16x16x32_bf16 v[108:111], v[158:161], v[198:201], v[108:111]
	v_mfma_f32_16x16x32_bf16 v[104:107], v[166:169], v[198:201], v[104:107]
	v_mfma_f32_16x16x32_bf16 v[92:95], v[158:161], v[206:209], v[92:95]
	v_mfma_f32_16x16x32_bf16 v[88:91], v[166:169], v[206:209], v[88:91]
	v_mfma_f32_16x16x32_bf16 v[76:79], v[158:161], v[214:217], v[76:79]
	v_mfma_f32_16x16x32_bf16 v[72:75], v[166:169], v[214:217], v[72:75]
	s_setprio 0
	s_setprio 1
	v_mfma_f32_16x16x32_bf16 v[116:119], v[170:173], v[186:189], v[116:119]
	v_mfma_f32_16x16x32_bf16 v[112:115], v[178:181], v[186:189], v[112:115]
	v_mfma_f32_16x16x32_bf16 v[100:103], v[170:173], v[194:197], v[100:103]
	v_mfma_f32_16x16x32_bf16 v[96:99], v[178:181], v[194:197], v[96:99]
	v_mfma_f32_16x16x32_bf16 v[84:87], v[170:173], v[202:205], v[84:87]
	v_mfma_f32_16x16x32_bf16 v[80:83], v[178:181], v[202:205], v[80:83]
	v_mfma_f32_16x16x32_bf16 v[68:71], v[170:173], v[210:213], v[68:71]
	v_mfma_f32_16x16x32_bf16 v[64:67], v[178:181], v[210:213], v[64:67]
	v_mfma_f32_16x16x32_bf16 v[116:119], v[174:177], v[190:193], v[116:119]
	v_mfma_f32_16x16x32_bf16 v[112:115], v[182:185], v[190:193], v[112:115]
	v_mfma_f32_16x16x32_bf16 v[100:103], v[174:177], v[198:201], v[100:103]
	v_mfma_f32_16x16x32_bf16 v[96:99], v[182:185], v[198:201], v[96:99]
	v_mfma_f32_16x16x32_bf16 v[84:87], v[174:177], v[206:209], v[84:87]
	v_mfma_f32_16x16x32_bf16 v[80:83], v[182:185], v[206:209], v[80:83]
	v_mfma_f32_16x16x32_bf16 v[68:71], v[174:177], v[214:217], v[68:71]
	v_mfma_f32_16x16x32_bf16 v[64:67], v[182:185], v[214:217], v[64:67]
	s_setprio 0
	s_barrier
; #define PG8_STAGE(bufoff, gbase, voff) do { _Pragma("unroll") for (int _i = 0; _i < 2; ++_i) { unsigned vo_ = (voff)[_i]; if constexpr (FP8) asm volatile("" : "+v"(vo_)); \
;         __builtin_amdgcn_global_load_lds((const unsigned*)((const char*)(gbase) + vo_), (PG8_LAS unsigned*)(lds + (bufoff) + ldsw + _i * 8192), 16, 0, 0); } } while (0)
; #define PG8_LDA(dst, b, h) do { _Pragma("unroll") for (int m = 0; m < 4; ++m) _Pragma("unroll") for (int k = 0; k < 2; ++k) dst[m][k] = *(const PG8_LAS bf16x8*)(lds + PG8_SA(b, h) + aoff + m * 2048 + k * 1024); } while (0)
; #define PG8_WAIT_V(n) asm volatile("s_waitcnt vmcnt(" #n ")" ::: "memory")
; #define PG8_WAIT_L(n) asm volatile("s_waitcnt lgkmcnt(" #n ")" ::: "memory")
; #define PG8_BAR __builtin_amdgcn_s_barrier()
; #define PG8_SCHED __builtin_amdgcn_sched_barrier(0)
; template <class Epi, class Sched, bool ALIGN_EPI = false, bool SP2 = false, bool FP8 = false>
; __device__ __forceinline__ void gemm_phase(PG8_LAS unsigned char* lds, const Gemm g, const Sched& S, const Epi& E) {
;     ...
;             PG8_LDA(At, 1, 1); PG8_STAGE(PG8_SB(1, 0), b3, voffB); PG8_STAGE(PG8_SB(1, 1), b3 + hstep, voffB); PG8_STAGE(PG8_SA(1, 0), a3, voffA);
;             PG8_WAIT_V(8); PG8_WAIT_L(0); PG8_BAR; PG8_MMA(1, 0, At, B0); PG8_MMA(1, 1, At, B1); PG8_BAR; PG8_SCHED;
	s_add_i32 s0, s62, s46
	v_lshl_add_u64 v[218:219], v[218:219], 0, s[8:9]
	s_mov_b32 m0, s0
	ds_read_b128 v[186:189], v155 offset:49152
	ds_read_b128 v[190:193], v155 offset:50176
	ds_read_b128 v[194:197], v155 offset:51200
	ds_read_b128 v[198:201], v155 offset:52224
	ds_read_b128 v[202:205], v155 offset:53248
	ds_read_b128 v[206:209], v155 offset:54272
	ds_read_b128 v[210:213], v155 offset:55296
	ds_read_b128 v[214:217], v155 offset:56320
	global_load_lds_dwordx4 v[218:219], off
	s_add_i32 m0, s0, 0x2000
	s_add_u32 s0, s42, 0x40080
	v_lshl_add_u64 v[218:219], v[220:221], 0, s[8:9]
	s_addc_u32 s1, s43, 0
	s_add_i32 s42, s63, s46
	global_load_lds_dwordx4 v[218:219], off
	v_lshl_add_u64 v[218:219], s[0:1], 0, v[132:133]
	s_mov_b32 m0, s42
	s_nop 0
	global_load_lds_dwordx4 v[218:219], off
	v_lshl_add_u64 v[218:219], s[0:1], 0, v[128:129]
	s_add_i32 m0, s42, 0x2000
	s_nop 0
	global_load_lds_dwordx4 v[218:219], off
	v_lshl_add_u64 v[218:219], v[222:223], 0, s[8:9]
	s_mov_b32 m0, s52
	s_nop 0
	global_load_lds_dwordx4 v[218:219], off
	v_lshl_add_u64 v[218:219], v[224:225], 0, s[8:9]
	s_mov_b32 m0, s53
	s_nop 0
	global_load_lds_dwordx4 v[218:219], off
	s_waitcnt vmcnt(8)
	s_waitcnt lgkmcnt(0)
	s_barrier
	s_setprio 1
	v_mfma_f32_16x16x32_bf16 v[60:63], v[146:149], v[186:189], v[60:63]
	v_mfma_f32_16x16x32_bf16 v[56:59], v[162:165], v[186:189], v[56:59]
	v_mfma_f32_16x16x32_bf16 v[44:47], v[146:149], v[194:197], v[44:47]
	v_mfma_f32_16x16x32_bf16 v[40:43], v[162:165], v[194:197], v[40:43]
	v_mfma_f32_16x16x32_bf16 v[28:31], v[146:149], v[202:205], v[28:31]
	v_mfma_f32_16x16x32_bf16 v[24:27], v[162:165], v[202:205], v[24:27]
	v_mfma_f32_16x16x32_bf16 v[12:15], v[146:149], v[210:213], v[12:15]
	v_mfma_f32_16x16x32_bf16 v[8:11], v[162:165], v[210:213], v[8:11]
	v_mfma_f32_16x16x32_bf16 v[60:63], v[158:161], v[190:193], v[60:63]
	v_mfma_f32_16x16x32_bf16 v[56:59], v[166:169], v[190:193], v[56:59]
	v_mfma_f32_16x16x32_bf16 v[44:47], v[158:161], v[198:201], v[44:47]
	v_mfma_f32_16x16x32_bf16 v[40:43], v[166:169], v[198:201], v[40:43]
	v_mfma_f32_16x16x32_bf16 v[28:31], v[158:161], v[206:209], v[28:31]
	v_mfma_f32_16x16x32_bf16 v[24:27], v[166:169], v[206:209], v[24:27]
	v_mfma_f32_16x16x32_bf16 v[12:15], v[158:161], v[214:217], v[12:15]
	v_mfma_f32_16x16x32_bf16 v[8:11], v[166:169], v[214:217], v[8:11]
	s_setprio 0
	s_setprio 1
	v_mfma_f32_16x16x32_bf16 v[52:55], v[170:173], v[186:189], v[52:55]
	v_mfma_f32_16x16x32_bf16 v[48:51], v[178:181], v[186:189], v[48:51]
	v_mfma_f32_16x16x32_bf16 v[36:39], v[170:173], v[194:197], v[36:39]
	v_mfma_f32_16x16x32_bf16 v[32:35], v[178:181], v[194:197], v[32:35]
	v_mfma_f32_16x16x32_bf16 v[20:23], v[170:173], v[202:205], v[20:23]
	v_mfma_f32_16x16x32_bf16 v[16:19], v[178:181], v[202:205], v[16:19]
	v_mfma_f32_16x16x32_bf16 v[4:7], v[170:173], v[210:213], v[4:7]
	v_mfma_f32_16x16x32_bf16 v[0:3], v[178:181], v[210:213], v[0:3]
	v_mfma_f32_16x16x32_bf16 v[52:55], v[174:177], v[190:193], v[52:55]
	v_mfma_f32_16x16x32_bf16 v[48:51], v[182:185], v[190:193], v[48:51]
	v_mfma_f32_16x16x32_bf16 v[36:39], v[174:177], v[198:201], v[36:39]
	v_mfma_f32_16x16x32_bf16 v[32:35], v[182:185], v[198:201], v[32:35]
	v_mfma_f32_16x16x32_bf16 v[20:23], v[174:177], v[206:209], v[20:23]
	v_mfma_f32_16x16x32_bf16 v[16:19], v[182:185], v[206:209], v[16:19]
	v_mfma_f32_16x16x32_bf16 v[4:7], v[174:177], v[214:217], v[4:7]
	v_mfma_f32_16x16x32_bf16 v[0:3], v[182:185], v[214:217], v[0:3]
	s_setprio 0
	s_barrier
	s_add_i32 s61, s61, 2
	s_add_u32 s40, s40, 0x100
	s_addc_u32 s41, s41, 0
	s_add_u32 s59, s59, 0x100
	s_addc_u32 s60, s60, 0
	s_cmp_gt_u32 s61, 13
	s_cbranch_scc0 .LBB0_391
	s_and_b64 vcc, exec, s[10:11]
	s_cbranch_vccz .LBB0_394
	s_barrier

; #define PG8_STAGE(bufoff, gbase, voff) do { _Pragma("unroll") for (int _i = 0; _i < 2; ++_i) { unsigned vo_ = (voff)[_i]; if constexpr (FP8) asm volatile("" : "+v"(vo_)); \
;         __builtin_amdgcn_global_load_lds((const unsigned*)((const char*)(gbase) + vo_), (PG8_LAS unsigned*)(lds + (bufoff) + ldsw + _i * 8192), 16, 0, 0); } } while (0)
; #define PG8_LDA(dst, b, h) do { _Pragma("unroll") for (int m = 0; m < 4; ++m) _Pragma("unroll") for (int k = 0; k < 2; ++k) dst[m][k] = *(const PG8_LAS bf16x8*)(lds + PG8_SA(b, h) + aoff + m * 2048 + k * 1024); } while (0)
; #define PG8_LDB(dst, b, h) do { _Pragma("unroll") for (int n = 0; n < 2; ++n) _Pragma("unroll") for (int k = 0; k < 2; ++k) dst[n][k] = *(const PG8_LAS bf16x8*)(lds + PG8_SB(b, h) + boff + n * 2048 + k * 1024); } while (0)
; #define PG8_WAIT_V(n) asm volatile("s_waitcnt vmcnt(" #n ")" ::: "memory")
; #define PG8_WAIT_L(n) asm volatile("s_waitcnt lgkmcnt(" #n ")" ::: "memory")
; #define PG8_BAR __builtin_amdgcn_s_barrier()
; #define PG8_SCHED __builtin_amdgcn_sched_barrier(0)
; template <class Epi, class Sched, bool ALIGN_EPI = false, bool SP2 = false, bool FP8 = false>
; __device__ __forceinline__ void gemm_phase(PG8_LAS unsigned char* lds, const Gemm g, const Sched& S, const Epi& E) {
;     ...
;             PG8_LDB(B0, 0, 0); PG8_LDB(B1, 0, 1); PG8_SCHED; PG8_LDA(At, 0, 0); PG8_STAGE(PG8_SA(1, 1), a1 + hstep, voffA);
;             PG8_WAIT_V(8); PG8_WAIT_L(0); PG8_BAR; PG8_MMA(0, 0, At, B0); PG8_MMA(0, 1, At, B1); PG8_BAR; PG8_SCHED;
;             PG8_LDA(At, 0, 1); PG8_STAGE(PG8_SB(0, 0), b2, voffB); PG8_STAGE(PG8_SB(0, 1), b2 + hstep, voffB); PG8_STAGE(PG8_SA(0, 0), a2, voffA);
;             PG8_WAIT_V(8); PG8_WAIT_L(0); PG8_BAR; PG8_MMA(1, 0, At, B0); PG8_MMA(1, 1, At, B1); PG8_BAR; PG8_SCHED;
.Lmy_nobar_P6:
.LBB0_427:
	ds_read_b128 v[128:131], v201
	ds_read_b128 v[132:135], v201 offset:1024
	ds_read_b128 v[136:139], v201 offset:2048
	ds_read_b128 v[140:143], v201 offset:3072
	ds_read_b128 v[144:147], v202
	ds_read_b128 v[148:151], v202 offset:1024
	ds_read_b128 v[170:173], v202 offset:2048
	ds_read_b128 v[174:177], v202 offset:3072
	s_add_u32 s42, s40, 0xfff00080
	s_addc_u32 s43, s41, -1
	s_cmp_eq_u32 s63, 60
	s_cselect_b32 s45, s31, s43
	s_cselect_b32 s44, s39, s42
	s_cselect_b32 s43, s23, s62
	s_cselect_b32 s42, s60, s61
	v_lshl_add_u64 v[218:219], s[40:41], 0, v[162:163]
	s_add_i32 m0, s47, 0xc000
	ds_read_b128 v[178:181], v203
	ds_read_b128 v[182:185], v203 offset:1024
	ds_read_b128 v[186:189], v203 offset:2048
	ds_read_b128 v[190:193], v203 offset:3072
	ds_read_b128 v[194:197], v203 offset:4096
	ds_read_b128 v[206:209], v203 offset:5120
	ds_read_b128 v[210:213], v203 offset:6144
	ds_read_b128 v[214:217], v203 offset:7168
	global_load_lds_dwordx4 v[218:219], off
	v_lshl_add_u64 v[218:219], s[40:41], 0, v[164:165]
	s_add_i32 m0, s47, 0xe000
	s_nop 0
	global_load_lds_dwordx4 v[218:219], off
	s_waitcnt vmcnt(8)
	s_waitcnt lgkmcnt(0)
	s_barrier
	s_setprio 1
	v_mfma_f32_16x16x32_bf16 v[124:127], v[128:131], v[178:181], v[124:127]
	v_mfma_f32_16x16x32_bf16 v[120:123], v[136:139], v[178:181], v[120:123]
	v_mfma_f32_16x16x32_bf16 v[108:111], v[128:131], v[186:189], v[108:111]
	v_mfma_f32_16x16x32_bf16 v[104:107], v[136:139], v[186:189], v[104:107]
	v_mfma_f32_16x16x32_bf16 v[92:95], v[128:131], v[194:197], v[92:95]
	v_mfma_f32_16x16x32_bf16 v[88:91], v[136:139], v[194:197], v[88:91]
	v_mfma_f32_16x16x32_bf16 v[76:79], v[128:131], v[210:213], v[76:79]
	v_mfma_f32_16x16x32_bf16 v[72:75], v[136:139], v[210:213], v[72:75]
	v_mfma_f32_16x16x32_bf16 v[124:127], v[132:135], v[182:185], v[124:127]
	v_mfma_f32_16x16x32_bf16 v[120:123], v[140:143], v[182:185], v[120:123]
	v_mfma_f32_16x16x32_bf16 v[108:111], v[132:135], v[190:193], v[108:111]
	v_mfma_f32_16x16x32_bf16 v[104:107], v[140:143], v[190:193], v[104:107]
	v_mfma_f32_16x16x32_bf16 v[92:95], v[132:135], v[206:209], v[92:95]
	v_mfma_f32_16x16x32_bf16 v[88:91], v[140:143], v[206:209], v[88:91]
	v_mfma_f32_16x16x32_bf16 v[76:79], v[132:135], v[214:217], v[76:79]
	v_mfma_f32_16x16x32_bf16 v[72:75], v[140:143], v[214:217], v[72:75]
	s_setprio 0
	s_setprio 1
	v_mfma_f32_16x16x32_bf16 v[116:119], v[144:147], v[178:181], v[116:119]
	v_mfma_f32_16x16x32_bf16 v[112:115], v[170:173], v[178:181], v[112:115]
	v_mfma_f32_16x16x32_bf16 v[100:103], v[144:147], v[186:189], v[100:103]
	v_mfma_f32_16x16x32_bf16 v[96:99], v[170:173], v[186:189], v[96:99]
	v_mfma_f32_16x16x32_bf16 v[84:87], v[144:147], v[194:197], v[84:87]
	v_mfma_f32_16x16x32_bf16 v[80:83], v[170:173], v[194:197], v[80:83]
	v_mfma_f32_16x16x32_bf16 v[68:71], v[144:147], v[210:213], v[68:71]
	v_mfma_f32_16x16x32_bf16 v[64:67], v[170:173], v[210:213], v[64:67]
	v_mfma_f32_16x16x32_bf16 v[116:119], v[148:151], v[182:185], v[116:119]
	v_mfma_f32_16x16x32_bf16 v[112:115], v[174:177], v[182:185], v[112:115]
	v_mfma_f32_16x16x32_bf16 v[100:103], v[148:151], v[190:193], v[100:103]
	v_mfma_f32_16x16x32_bf16 v[96:99], v[174:177], v[190:193], v[96:99]
	v_mfma_f32_16x16x32_bf16 v[84:87], v[148:151], v[206:209], v[84:87]
	v_mfma_f32_16x16x32_bf16 v[80:83], v[174:177], v[206:209], v[80:83]
	v_mfma_f32_16x16x32_bf16 v[68:71], v[148:151], v[214:217], v[68:71]
	v_mfma_f32_16x16x32_bf16 v[64:67], v[174:177], v[214:217], v[64:67]
	s_setprio 0
	s_barrier
	s_add_i32 s64, s57, s46
	v_lshl_add_u64 v[218:219], s[42:43], 0, v[154:155]
	s_mov_b32 m0, s64
	ds_read_b128 v[178:181], v203 offset:16384
	ds_read_b128 v[182:185], v203 offset:17408
	ds_read_b128 v[186:189], v203 offset:18432
	ds_read_b128 v[190:193], v203 offset:19456
	ds_read_b128 v[194:197], v203 offset:20480
	ds_read_b128 v[206:209], v203 offset:21504
	ds_read_b128 v[210:213], v203 offset:22528
	ds_read_b128 v[214:217], v203 offset:23552
	global_load_lds_dwordx4 v[218:219], off
	s_add_i32 m0, s64, 0x2000
	s_add_u32 s64, s42, 0x100000
	v_lshl_add_u64 v[220:221], s[42:43], 0, v[158:159]
	s_addc_u32 s65, s43, 0
	s_add_i32 s66, s58, s46
	global_load_lds_dwordx4 v[220:221], off
	v_lshl_add_u64 v[222:223], s[64:65], 0, v[154:155]
	s_mov_b32 m0, s66
	v_lshl_add_u64 v[224:225], s[44:45], 0, v[156:157]
	global_load_lds_dwordx4 v[222:223], off
	v_lshl_add_u64 v[222:223], s[64:65], 0, v[158:159]
	s_add_i32 m0, s66, 0x2000
	s_nop 0
	global_load_lds_dwordx4 v[222:223], off
	v_lshl_add_u64 v[222:223], s[44:45], 0, v[152:153]
	s_mov_b32 m0, s47
	s_nop 0
	global_load_lds_dwordx4 v[222:223], off
	s_mov_b32 m0, s48
	s_nop 0
	global_load_lds_dwordx4 v[224:225], off
	s_waitcnt vmcnt(8)
	s_waitcnt lgkmcnt(0)
	s_barrier
; #define PG8_STAGE(bufoff, gbase, voff) do { _Pragma("unroll") for (int _i = 0; _i < 2; ++_i) { unsigned vo_ = (voff)[_i]; if constexpr (FP8) asm volatile("" : "+v"(vo_)); \
;         __builtin_amdgcn_global_load_lds((const unsigned*)((const char*)(gbase) + vo_), (PG8_LAS unsigned*)(lds + (bufoff) + ldsw + _i * 8192), 16, 0, 0); } } while (0)
; #define PG8_LDA(dst, b, h) do { _Pragma("unroll") for (int m = 0; m < 4; ++m) _Pragma("unroll") for (int k = 0; k < 2; ++k) dst[m][k] = *(const PG8_LAS bf16x8*)(lds + PG8_SA(b, h) + aoff + m * 2048 + k * 1024); } while (0)
; #define PG8_LDB(dst, b, h) do { _Pragma("unroll") for (int n = 0; n < 2; ++n) _Pragma("unroll") for (int k = 0; k < 2; ++k) dst[n][k] = *(const PG8_LAS bf16x8*)(lds + PG8_SB(b, h) + boff + n * 2048 + k * 1024); } while (0)
; #define PG8_WAIT_V(n) asm volatile("s_waitcnt vmcnt(" #n ")" ::: "memory")
; #define PG8_WAIT_L(n) asm volatile("s_waitcnt lgkmcnt(" #n ")" ::: "memory")
; #define PG8_BAR __builtin_amdgcn_s_barrier()
; #define PG8_SCHED __builtin_amdgcn_sched_barrier(0)
; template <class Epi, class Sched, bool ALIGN_EPI = false, bool SP2 = false, bool FP8 = false>
; __device__ __forceinline__ void gemm_phase(PG8_LAS unsigned char* lds, const Gemm g, const Sched& S, const Epi& E) {
;     ...
;             PG8_WAIT_V(8); PG8_WAIT_L(0); PG8_BAR; PG8_MMA(1, 0, At, B0); PG8_MMA(1, 1, At, B1); PG8_BAR; PG8_SCHED;
;             PG8_LDB(B0, 1, 0); PG8_LDB(B1, 1, 1); PG8_SCHED; PG8_LDA(At, 1, 0); PG8_STAGE(PG8_SA(0, 1), a2 + hstep, voffA);
;             PG8_WAIT_V(8); PG8_WAIT_L(0); PG8_BAR; PG8_MMA(0, 0, At, B0); PG8_MMA(0, 1, At, B1); PG8_BAR; PG8_SCHED;
;             PG8_LDA(At, 1, 1); PG8_STAGE(PG8_SB(1, 0), b3, voffB); PG8_STAGE(PG8_SB(1, 1), b3 + hstep, voffB); PG8_STAGE(PG8_SA(1, 0), a3, voffA);
	s_setprio 1
	v_mfma_f32_16x16x32_bf16 v[60:63], v[128:131], v[178:181], v[60:63]
	v_mfma_f32_16x16x32_bf16 v[56:59], v[136:139], v[178:181], v[56:59]
	v_mfma_f32_16x16x32_bf16 v[44:47], v[128:131], v[186:189], v[44:47]
	v_mfma_f32_16x16x32_bf16 v[40:43], v[136:139], v[186:189], v[40:43]
	v_mfma_f32_16x16x32_bf16 v[28:31], v[128:131], v[194:197], v[28:31]
	v_mfma_f32_16x16x32_bf16 v[24:27], v[136:139], v[194:197], v[24:27]
	v_mfma_f32_16x16x32_bf16 v[12:15], v[128:131], v[210:213], v[12:15]
	v_mfma_f32_16x16x32_bf16 v[8:11], v[136:139], v[210:213], v[8:11]
	v_mfma_f32_16x16x32_bf16 v[60:63], v[132:135], v[182:185], v[60:63]
	v_mfma_f32_16x16x32_bf16 v[56:59], v[140:143], v[182:185], v[56:59]
	v_mfma_f32_16x16x32_bf16 v[44:47], v[132:135], v[190:193], v[44:47]
	v_mfma_f32_16x16x32_bf16 v[40:43], v[140:143], v[190:193], v[40:43]
	v_mfma_f32_16x16x32_bf16 v[28:31], v[132:135], v[206:209], v[28:31]
	v_mfma_f32_16x16x32_bf16 v[24:27], v[140:143], v[206:209], v[24:27]
	v_mfma_f32_16x16x32_bf16 v[12:15], v[132:135], v[214:217], v[12:15]
	v_mfma_f32_16x16x32_bf16 v[8:11], v[140:143], v[214:217], v[8:11]
	s_setprio 0
	s_setprio 1
	v_mfma_f32_16x16x32_bf16 v[52:55], v[144:147], v[178:181], v[52:55]
	v_mfma_f32_16x16x32_bf16 v[48:51], v[170:173], v[178:181], v[48:51]
	v_mfma_f32_16x16x32_bf16 v[36:39], v[144:147], v[186:189], v[36:39]
	v_mfma_f32_16x16x32_bf16 v[32:35], v[170:173], v[186:189], v[32:35]
	v_mfma_f32_16x16x32_bf16 v[20:23], v[144:147], v[194:197], v[20:23]
	v_mfma_f32_16x16x32_bf16 v[16:19], v[170:173], v[194:197], v[16:19]
	v_mfma_f32_16x16x32_bf16 v[4:7], v[144:147], v[210:213], v[4:7]
	v_mfma_f32_16x16x32_bf16 v[0:3], v[170:173], v[210:213], v[0:3]
	v_mfma_f32_16x16x32_bf16 v[52:55], v[148:151], v[182:185], v[52:55]
	v_mfma_f32_16x16x32_bf16 v[48:51], v[174:177], v[182:185], v[48:51]
	v_mfma_f32_16x16x32_bf16 v[36:39], v[148:151], v[190:193], v[36:39]
	v_mfma_f32_16x16x32_bf16 v[32:35], v[174:177], v[190:193], v[32:35]
	v_mfma_f32_16x16x32_bf16 v[20:23], v[148:151], v[206:209], v[20:23]
	v_mfma_f32_16x16x32_bf16 v[16:19], v[174:177], v[206:209], v[16:19]
	v_mfma_f32_16x16x32_bf16 v[4:7], v[148:151], v[214:217], v[4:7]
	v_mfma_f32_16x16x32_bf16 v[0:3], v[174:177], v[214:217], v[0:3]
	s_setprio 0
	s_barrier
	s_add_i32 s64, 0, 0x18000
	s_add_i32 s65, 0, 0x1c000
	v_add_u32_e32 v140, s64, v199
	v_add_u32_e32 v174, s65, v199
	ds_read_b128 v[128:131], v140
	ds_read_b128 v[132:135], v140 offset:1024
	ds_read_b128 v[136:139], v140 offset:2048
	ds_read_b128 v[140:143], v140 offset:3072
	ds_read_b128 v[144:147], v174
	ds_read_b128 v[148:151], v174 offset:1024
	ds_read_b128 v[170:173], v174 offset:2048
	ds_read_b128 v[174:177], v174 offset:3072
	s_add_u32 s44, s44, 0x100000
	s_addc_u32 s45, s45, 0
	s_mov_b32 m0, s49
	v_lshl_add_u64 v[226:227], s[44:45], 0, v[152:153]
	ds_read_b128 v[178:181], v203 offset:32768
	ds_read_b128 v[182:185], v203 offset:33792
	ds_read_b128 v[186:189], v203 offset:34816
	ds_read_b128 v[190:193], v203 offset:35840
	ds_read_b128 v[194:197], v203 offset:36864
	ds_read_b128 v[206:209], v203 offset:37888
	ds_read_b128 v[210:213], v203 offset:38912
	ds_read_b128 v[214:217], v203 offset:39936
	global_load_lds_dwordx4 v[226:227], off
	v_lshl_add_u64 v[226:227], s[44:45], 0, v[156:157]
	s_mov_b32 m0, s50
	s_nop 0
	global_load_lds_dwordx4 v[226:227], off
	s_waitcnt vmcnt(8)
	s_waitcnt lgkmcnt(0)
	s_barrier
	s_setprio 1
	v_mfma_f32_16x16x32_bf16 v[124:127], v[128:131], v[178:181], v[124:127]
	v_mfma_f32_16x16x32_bf16 v[120:123], v[136:139], v[178:181], v[120:123]
	v_mfma_f32_16x16x32_bf16 v[108:111], v[128:131], v[186:189], v[108:111]
	v_mfma_f32_16x16x32_bf16 v[104:107], v[136:139], v[186:189], v[104:107]
	v_mfma_f32_16x16x32_bf16 v[92:95], v[128:131], v[194:197], v[92:95]
	v_mfma_f32_16x16x32_bf16 v[88:91], v[136:139], v[194:197], v[88:91]
	v_mfma_f32_16x16x32_bf16 v[76:79], v[128:131], v[210:213], v[76:79]
	v_mfma_f32_16x16x32_bf16 v[72:75], v[136:139], v[210:213], v[72:75]
	v_mfma_f32_16x16x32_bf16 v[124:127], v[132:135], v[182:185], v[124:127]
	v_mfma_f32_16x16x32_bf16 v[120:123], v[140:143], v[182:185], v[120:123]
	v_mfma_f32_16x16x32_bf16 v[108:111], v[132:135], v[190:193], v[108:111]
	v_mfma_f32_16x16x32_bf16 v[104:107], v[140:143], v[190:193], v[104:107]
	v_mfma_f32_16x16x32_bf16 v[92:95], v[132:135], v[206:209], v[92:95]
	v_mfma_f32_16x16x32_bf16 v[88:91], v[140:143], v[206:209], v[88:91]
	v_mfma_f32_16x16x32_bf16 v[76:79], v[132:135], v[214:217], v[76:79]
	v_mfma_f32_16x16x32_bf16 v[72:75], v[140:143], v[214:217], v[72:75]
	s_setprio 0
	s_setprio 1
	v_mfma_f32_16x16x32_bf16 v[116:119], v[144:147], v[178:181], v[116:119]
	v_mfma_f32_16x16x32_bf16 v[112:115], v[170:173], v[178:181], v[112:115]
	v_mfma_f32_16x16x32_bf16 v[100:103], v[144:147], v[186:189], v[100:103]
	v_mfma_f32_16x16x32_bf16 v[96:99], v[170:173], v[186:189], v[96:99]
	v_mfma_f32_16x16x32_bf16 v[84:87], v[144:147], v[194:197], v[84:87]
	v_mfma_f32_16x16x32_bf16 v[80:83], v[170:173], v[194:197], v[80:83]
	v_mfma_f32_16x16x32_bf16 v[68:71], v[144:147], v[210:213], v[68:71]
	v_mfma_f32_16x16x32_bf16 v[64:67], v[170:173], v[210:213], v[64:67]
	v_mfma_f32_16x16x32_bf16 v[116:119], v[148:151], v[182:185], v[116:119]
	v_mfma_f32_16x16x32_bf16 v[112:115], v[174:177], v[182:185], v[112:115]
	v_mfma_f32_16x16x32_bf16 v[100:103], v[148:151], v[190:193], v[100:103]
	v_mfma_f32_16x16x32_bf16 v[96:99], v[174:177], v[190:193], v[96:99]
	v_mfma_f32_16x16x32_bf16 v[84:87], v[148:151], v[206:209], v[84:87]
	v_mfma_f32_16x16x32_bf16 v[80:83], v[174:177], v[206:209], v[80:83]
	v_mfma_f32_16x16x32_bf16 v[68:71], v[148:151], v[214:217], v[68:71]
	v_mfma_f32_16x16x32_bf16 v[64:67], v[174:177], v[214:217], v[64:67]
	s_setprio 0
	s_barrier
; #define PG8_STAGE(bufoff, gbase, voff) do { _Pragma("unroll") for (int _i = 0; _i < 2; ++_i) { unsigned vo_ = (voff)[_i]; if constexpr (FP8) asm volatile("" : "+v"(vo_)); \
;         __builtin_amdgcn_global_load_lds((const unsigned*)((const char*)(gbase) + vo_), (PG8_LAS unsigned*)(lds + (bufoff) + ldsw + _i * 8192), 16, 0, 0); } } while (0)
; #define PG8_LDA(dst, b, h) do { _Pragma("unroll") for (int m = 0; m < 4; ++m) _Pragma("unroll") for (int k = 0; k < 2; ++k) dst[m][k] = *(const PG8_LAS bf16x8*)(lds + PG8_SA(b, h) + aoff + m * 2048 + k * 1024); } while (0)
; #define PG8_WAIT_V(n) asm volatile("s_waitcnt vmcnt(" #n ")" ::: "memory")
; #define PG8_WAIT_L(n) asm volatile("s_waitcnt lgkmcnt(" #n ")" ::: "memory")
; #define PG8_BAR __builtin_amdgcn_s_barrier()
; #define PG8_SCHED __builtin_amdgcn_sched_barrier(0)
; template <class Epi, class Sched, bool ALIGN_EPI = false, bool SP2 = false, bool FP8 = false>
; __device__ __forceinline__ void gemm_phase(PG8_LAS unsigned char* lds, const Gemm g, const Sched& S, const Epi& E) {
;     ...
;         for (int t = 0; t < nt; t += 2) {
;     ...
;             PG8_LDA(At, 1, 1); PG8_STAGE(PG8_SB(1, 0), b3, voffB); PG8_STAGE(PG8_SB(1, 1), b3 + hstep, voffB); PG8_STAGE(PG8_SA(1, 0), a3, voffA);
;             PG8_WAIT_V(8); PG8_WAIT_L(0); PG8_BAR; PG8_MMA(1, 0, At, B0); PG8_MMA(1, 1, At, B1); PG8_BAR; PG8_SCHED;
	s_add_i32 s44, s64, s46
	v_lshl_add_u64 v[218:219], v[218:219], 0, s[12:13]
	s_mov_b32 m0, s44
	ds_read_b128 v[178:181], v203 offset:49152
	ds_read_b128 v[182:185], v203 offset:50176
	ds_read_b128 v[186:189], v203 offset:51200
	ds_read_b128 v[190:193], v203 offset:52224
	ds_read_b128 v[194:197], v203 offset:53248
	ds_read_b128 v[206:209], v203 offset:54272
	ds_read_b128 v[210:213], v203 offset:55296
	ds_read_b128 v[214:217], v203 offset:56320
	global_load_lds_dwordx4 v[218:219], off
	s_add_i32 m0, s44, 0x2000
	s_add_u32 s42, s42, 0x100080
	v_lshl_add_u64 v[218:219], v[220:221], 0, s[12:13]
	s_addc_u32 s43, s43, 0
	s_add_i32 s44, s65, s46
	global_load_lds_dwordx4 v[218:219], off
	v_lshl_add_u64 v[218:219], s[42:43], 0, v[154:155]
	s_mov_b32 m0, s44
	s_nop 0
	global_load_lds_dwordx4 v[218:219], off
	v_lshl_add_u64 v[218:219], s[42:43], 0, v[158:159]
	s_add_i32 m0, s44, 0x2000
	s_nop 0
	global_load_lds_dwordx4 v[218:219], off
	v_lshl_add_u64 v[218:219], v[222:223], 0, s[12:13]
	s_mov_b32 m0, s54
	s_nop 0
	global_load_lds_dwordx4 v[218:219], off
	v_lshl_add_u64 v[218:219], v[224:225], 0, s[12:13]
	s_mov_b32 m0, s55
	s_nop 0
	global_load_lds_dwordx4 v[218:219], off
	s_waitcnt vmcnt(8)
	s_waitcnt lgkmcnt(0)
	s_barrier
	s_setprio 1
	v_mfma_f32_16x16x32_bf16 v[60:63], v[128:131], v[178:181], v[60:63]
	v_mfma_f32_16x16x32_bf16 v[56:59], v[136:139], v[178:181], v[56:59]
	v_mfma_f32_16x16x32_bf16 v[44:47], v[128:131], v[186:189], v[44:47]
	v_mfma_f32_16x16x32_bf16 v[40:43], v[136:139], v[186:189], v[40:43]
	v_mfma_f32_16x16x32_bf16 v[28:31], v[128:131], v[194:197], v[28:31]
	v_mfma_f32_16x16x32_bf16 v[24:27], v[136:139], v[194:197], v[24:27]
	v_mfma_f32_16x16x32_bf16 v[12:15], v[128:131], v[210:213], v[12:15]
	v_mfma_f32_16x16x32_bf16 v[8:11], v[136:139], v[210:213], v[8:11]
	v_mfma_f32_16x16x32_bf16 v[60:63], v[132:135], v[182:185], v[60:63]
	v_mfma_f32_16x16x32_bf16 v[56:59], v[140:143], v[182:185], v[56:59]
	v_mfma_f32_16x16x32_bf16 v[44:47], v[132:135], v[190:193], v[44:47]
	v_mfma_f32_16x16x32_bf16 v[40:43], v[140:143], v[190:193], v[40:43]
	v_mfma_f32_16x16x32_bf16 v[28:31], v[132:135], v[206:209], v[28:31]
	v_mfma_f32_16x16x32_bf16 v[24:27], v[140:143], v[206:209], v[24:27]
	v_mfma_f32_16x16x32_bf16 v[12:15], v[132:135], v[214:217], v[12:15]
	v_mfma_f32_16x16x32_bf16 v[8:11], v[140:143], v[214:217], v[8:11]
	s_setprio 0
	s_setprio 1
	v_mfma_f32_16x16x32_bf16 v[52:55], v[144:147], v[178:181], v[52:55]
	v_mfma_f32_16x16x32_bf16 v[48:51], v[170:173], v[178:181], v[48:51]
	v_mfma_f32_16x16x32_bf16 v[36:39], v[144:147], v[186:189], v[36:39]
	v_mfma_f32_16x16x32_bf16 v[32:35], v[170:173], v[186:189], v[32:35]
	v_mfma_f32_16x16x32_bf16 v[20:23], v[144:147], v[194:197], v[20:23]
	v_mfma_f32_16x16x32_bf16 v[16:19], v[170:173], v[194:197], v[16:19]
	v_mfma_f32_16x16x32_bf16 v[4:7], v[144:147], v[210:213], v[4:7]
	v_mfma_f32_16x16x32_bf16 v[0:3], v[170:173], v[210:213], v[0:3]
	v_mfma_f32_16x16x32_bf16 v[52:55], v[148:151], v[182:185], v[52:55]
	v_mfma_f32_16x16x32_bf16 v[48:51], v[174:177], v[182:185], v[48:51]
	v_mfma_f32_16x16x32_bf16 v[36:39], v[148:151], v[190:193], v[36:39]
	v_mfma_f32_16x16x32_bf16 v[32:35], v[174:177], v[190:193], v[32:35]
	v_mfma_f32_16x16x32_bf16 v[20:23], v[148:151], v[206:209], v[20:23]
	v_mfma_f32_16x16x32_bf16 v[16:19], v[174:177], v[206:209], v[16:19]
	v_mfma_f32_16x16x32_bf16 v[4:7], v[148:151], v[214:217], v[4:7]
	v_mfma_f32_16x16x32_bf16 v[0:3], v[174:177], v[214:217], v[0:3]
	s_setprio 0
	s_barrier
	s_add_i32 s63, s63, 2
	s_add_u32 s40, s40, 0x100
	s_addc_u32 s41, s41, 0
	s_add_u32 s61, s61, 0x100
	s_addc_u32 s62, s62, 0
	s_cmp_gt_u32 s63, 61
	s_cbranch_scc0 .LBB0_427
	s_and_b64 vcc, exec, s[14:15]
	s_cbranch_vccz .LBB0_430
